# v93 + 64-byte alignment of the hot loop heads (GEMM K loops, GLA chunk loops, RG-LRU tile loops, attention fast path)
# baseline (speedup 1.0000x reference)
.LBB0_305:
	s_ashr_i32 s19, s18, 31
	s_lshl_b64 s[22:23], s[18:19], 19
	s_add_u32 s22, s36, s22
	s_addc_u32 s23, s37, s23
	s_and_b64 s[24:25], s[2:3], exec
	s_cselect_b32 s5, s23, s27
	s_cselect_b32 s7, s22, s26
	s_ashr_i32 s21, s20, 31
	s_lshl_b64 s[24:25], s[20:21], 19
	s_add_u32 s24, s35, s24
	s_addc_u32 s25, s34, s25
	s_and_b64 s[30:31], s[2:3], exec
	s_cselect_b32 s19, s25, s29
	s_cselect_b32 s21, s24, s28
	s_add_u32 s26, s26, 0x40080
	s_addc_u32 s27, s27, 0
	s_add_u32 s56, s28, 0x100
	v_mov_b32_e32 v0, 0
	s_addc_u32 s57, s29, 0
	s_mov_b32 s58, -2
	v_mov_b32_e32 v1, v0
	v_mov_b32_e32 v2, v0
	v_mov_b32_e32 v3, v0
	v_mov_b32_e32 v4, v0
	v_mov_b32_e32 v5, v0
	v_mov_b32_e32 v6, v0
	v_mov_b32_e32 v7, v0
	v_mov_b32_e32 v16, v0
	v_mov_b32_e32 v17, v0
	v_mov_b32_e32 v18, v0
	v_mov_b32_e32 v19, v0
	v_mov_b32_e32 v20, v0
	v_mov_b32_e32 v21, v0
	v_mov_b32_e32 v22, v0
	v_mov_b32_e32 v23, v0
	v_mov_b32_e32 v32, v0
	v_mov_b32_e32 v33, v0
	v_mov_b32_e32 v34, v0
	v_mov_b32_e32 v35, v0
	v_mov_b32_e32 v36, v0
	v_mov_b32_e32 v37, v0
	v_mov_b32_e32 v38, v0
	v_mov_b32_e32 v39, v0
	v_mov_b32_e32 v48, v0
	v_mov_b32_e32 v49, v0
	v_mov_b32_e32 v50, v0
	v_mov_b32_e32 v51, v0
	v_mov_b32_e32 v52, v0
	v_mov_b32_e32 v53, v0
	v_mov_b32_e32 v54, v0
	v_mov_b32_e32 v55, v0
	v_mov_b32_e32 v8, v0
	v_mov_b32_e32 v9, v0
	v_mov_b32_e32 v10, v0
	v_mov_b32_e32 v11, v0
	v_mov_b32_e32 v12, v0
	v_mov_b32_e32 v13, v0
	v_mov_b32_e32 v14, v0
	v_mov_b32_e32 v15, v0
	v_mov_b32_e32 v24, v0
	v_mov_b32_e32 v25, v0
	v_mov_b32_e32 v26, v0
	v_mov_b32_e32 v27, v0
	v_mov_b32_e32 v28, v0
	v_mov_b32_e32 v29, v0
	v_mov_b32_e32 v30, v0
	v_mov_b32_e32 v31, v0
	v_mov_b32_e32 v40, v0
	v_mov_b32_e32 v41, v0
	v_mov_b32_e32 v42, v0
	v_mov_b32_e32 v43, v0
	v_mov_b32_e32 v44, v0
	v_mov_b32_e32 v45, v0
	v_mov_b32_e32 v46, v0
	v_mov_b32_e32 v47, v0
	v_mov_b32_e32 v56, v0
	v_mov_b32_e32 v57, v0
	v_mov_b32_e32 v58, v0
	v_mov_b32_e32 v59, v0
	v_mov_b32_e32 v60, v0
	v_mov_b32_e32 v61, v0
	v_mov_b32_e32 v62, v0
	v_mov_b32_e32 v63, v0
	v_mov_b32_e32 v64, v0
	v_mov_b32_e32 v65, v0
	v_mov_b32_e32 v66, v0
	v_mov_b32_e32 v67, v0
	v_mov_b32_e32 v68, v0
	v_mov_b32_e32 v69, v0
	v_mov_b32_e32 v70, v0
	v_mov_b32_e32 v71, v0
	v_mov_b32_e32 v80, v0
	v_mov_b32_e32 v81, v0
	v_mov_b32_e32 v82, v0
	v_mov_b32_e32 v83, v0
	v_mov_b32_e32 v84, v0
	v_mov_b32_e32 v85, v0
	v_mov_b32_e32 v86, v0
	v_mov_b32_e32 v87, v0
	v_mov_b32_e32 v96, v0
	v_mov_b32_e32 v97, v0
	v_mov_b32_e32 v98, v0
	v_mov_b32_e32 v99, v0
	v_mov_b32_e32 v100, v0
	v_mov_b32_e32 v101, v0
	v_mov_b32_e32 v102, v0
	v_mov_b32_e32 v103, v0
	v_mov_b32_e32 v112, v0
	v_mov_b32_e32 v113, v0
	v_mov_b32_e32 v114, v0
	v_mov_b32_e32 v115, v0
	v_mov_b32_e32 v116, v0
	v_mov_b32_e32 v117, v0
	v_mov_b32_e32 v118, v0
	v_mov_b32_e32 v119, v0
	v_mov_b32_e32 v72, v0
	v_mov_b32_e32 v73, v0
	v_mov_b32_e32 v74, v0
	v_mov_b32_e32 v75, v0
	v_mov_b32_e32 v76, v0
	v_mov_b32_e32 v77, v0
	v_mov_b32_e32 v78, v0
	v_mov_b32_e32 v79, v0
	v_mov_b32_e32 v88, v0
	v_mov_b32_e32 v89, v0
	v_mov_b32_e32 v90, v0
	v_mov_b32_e32 v91, v0
	v_mov_b32_e32 v92, v0
	v_mov_b32_e32 v93, v0
	v_mov_b32_e32 v94, v0
	v_mov_b32_e32 v95, v0
	v_mov_b32_e32 v104, v0
	v_mov_b32_e32 v105, v0
	v_mov_b32_e32 v106, v0
	v_mov_b32_e32 v107, v0
	v_mov_b32_e32 v108, v0
	v_mov_b32_e32 v109, v0
	v_mov_b32_e32 v110, v0
	v_mov_b32_e32 v111, v0
	v_mov_b32_e32 v120, v0
	v_mov_b32_e32 v121, v0
	v_mov_b32_e32 v122, v0
	v_mov_b32_e32 v123, v0
	v_mov_b32_e32 v124, v0
	v_mov_b32_e32 v125, v0
	v_mov_b32_e32 v126, v0
	v_mov_b32_e32 v127, v0
	.p2alignl 6, 3212836864

.LBB0_464:
	ds_read_b128 v[94:97], v149 offset:6144
	ds_read_b128 v[98:101], v149 offset:6160
	s_waitcnt vmcnt(5)
	v_lshlrev_b32_e32 v102, 16, v22
	v_and_b32_e32 v103, 0xffff0000, v22
	s_add_i32 s46, s47, s46
	s_waitcnt lgkmcnt(1)
	v_mul_f32_e32 v94, 0xbfb8aa3b, v94
	v_mul_f32_e32 v95, 0xbfb8aa3b, v95
	v_exp_f32_e32 v94, v94
	v_exp_f32_e32 v95, v95
	v_mul_f32_e32 v22, 0xbfb8aa3b, v96
	v_exp_f32_e32 v96, v22
	v_mul_f32_e32 v22, 0xbfb8aa3b, v97
	v_exp_f32_e32 v97, v22
	v_pk_mul_f32 v[94:95], v[94:95], v[102:103]
	s_add_i32 s83, s83, 1
	v_cvt_pk_bf16_f32 v22, v94, v95
	v_lshlrev_b32_e32 v94, 16, v23
	v_and_b32_e32 v95, 0xffff0000, v23
	s_waitcnt lgkmcnt(0)
	v_mul_f32_e32 v23, 0xbfb8aa3b, v98
	v_pk_mul_f32 v[94:95], v[96:97], v[94:95]
	v_exp_f32_e32 v96, v23
	v_mul_f32_e32 v23, 0xbfb8aa3b, v99
	v_exp_f32_e32 v97, v23
	v_cvt_pk_bf16_f32 v23, v94, v95
	v_lshlrev_b32_e32 v94, 16, v24
	v_and_b32_e32 v95, 0xffff0000, v24
	v_mul_f32_e32 v24, 0xbfb8aa3b, v100
	v_pk_mul_f32 v[94:95], v[96:97], v[94:95]
	v_exp_f32_e32 v96, v24
	v_mul_f32_e32 v24, 0xbfb8aa3b, v101
	v_exp_f32_e32 v97, v24
	v_cvt_pk_bf16_f32 v24, v94, v95
	v_lshlrev_b32_e32 v94, 16, v25
	v_and_b32_e32 v95, 0xffff0000, v25
	v_pk_mul_f32 v[94:95], v[96:97], v[94:95]
	s_waitcnt vmcnt(4)
	v_lshlrev_b32_e32 v98, 16, v6
	v_cvt_pk_bf16_f32 v25, v94, v95
	ds_write_b128 v150, v[22:25] offset:56320
	ds_read_b128 v[22:25], v151 offset:6144
	ds_read_b128 v[94:97], v151 offset:6160
	v_and_b32_e32 v99, 0xffff0000, v6
	s_mul_i32 s53, s46, 0x1800
	s_mul_hi_i32 s52, s46, 0x1800
	s_waitcnt lgkmcnt(1)
	v_mul_f32_e32 v22, 0xbfb8aa3b, v22
	v_mul_f32_e32 v23, 0xbfb8aa3b, v23
	v_exp_f32_e32 v22, v22
	v_exp_f32_e32 v23, v23
	v_mul_f32_e32 v6, 0xbfb8aa3b, v24
	v_exp_f32_e32 v24, v6
	v_mul_f32_e32 v6, 0xbfb8aa3b, v25
	v_exp_f32_e32 v25, v6
	v_pk_mul_f32 v[22:23], v[22:23], v[98:99]
	s_add_u32 s50, s80, s53
	v_cvt_pk_bf16_f32 v6, v22, v23
	v_lshlrev_b32_e32 v22, 16, v7
	v_and_b32_e32 v23, 0xffff0000, v7
	s_waitcnt lgkmcnt(0)
	v_mul_f32_e32 v7, 0xbfb8aa3b, v94
	v_pk_mul_f32 v[22:23], v[24:25], v[22:23]
	v_exp_f32_e32 v24, v7
	v_mul_f32_e32 v7, 0xbfb8aa3b, v95
	v_exp_f32_e32 v25, v7
	v_cvt_pk_bf16_f32 v7, v22, v23
	v_lshlrev_b32_e32 v22, 16, v8
	v_and_b32_e32 v23, 0xffff0000, v8
	v_mul_f32_e32 v8, 0xbfb8aa3b, v96
	v_pk_mul_f32 v[22:23], v[24:25], v[22:23]
	v_exp_f32_e32 v24, v8
	v_mul_f32_e32 v8, 0xbfb8aa3b, v97
	v_exp_f32_e32 v25, v8
	v_cvt_pk_bf16_f32 v8, v22, v23
	v_lshlrev_b32_e32 v22, 16, v9
	v_and_b32_e32 v23, 0xffff0000, v9
	v_pk_mul_f32 v[22:23], v[24:25], v[22:23]
	s_addc_u32 s51, s81, s52
	v_cvt_pk_bf16_f32 v9, v22, v23
	ds_write_b128 v152, v[6:9] offset:56320
	s_waitcnt vmcnt(3)
	ds_write_b128 v153, v[2:5]
	s_waitcnt vmcnt(2)
	ds_write_b128 v155, v[10:13]
	s_waitcnt vmcnt(1)
	ds_write_b128 v153, v[14:17] offset:16896
	s_waitcnt vmcnt(0)
	ds_write_b128 v156, v[18:21]
	v_lshl_add_u64 v[2:3], s[50:51], 0, v[112:113]
	s_add_u32 s50, s38, s53
	s_addc_u32 s51, s39, s52
	s_add_u32 s50, s50, s76
	s_addc_u32 s51, s51, 0
	s_add_u32 s50, s50, 0xad20800
	global_load_dwordx4 v[22:25], v[2:3], off offset:1024
	v_add_co_u32_e32 v2, vcc, s63, v2
	s_addc_u32 s51, s51, 0
	s_nop 0
	v_addc_co_u32_e32 v3, vcc, 0, v3, vcc
	v_lshl_add_u64 v[18:19], s[50:51], 0, v[114:115]
	v_add_co_u32_e32 v10, vcc, s64, v18
	global_load_dwordx4 v[6:9], v[2:3], off offset:1024
	s_nop 0
	v_addc_co_u32_e32 v11, vcc, 0, v19, vcc
	v_add_co_u32_e32 v14, vcc, s63, v18
	global_load_dwordx4 v[2:5], v[18:19], off
	s_nop 0
	v_addc_co_u32_e32 v15, vcc, 0, v19, vcc
	v_add_co_u32_e32 v18, vcc, s65, v18
	global_load_dwordx4 v[10:13], v[10:11], off
	s_nop 0
	v_addc_co_u32_e32 v19, vcc, 0, v19, vcc
	global_load_dwordx4 v[14:17], v[14:15], off
	v_lshl_add_u32 v167, s87, 9, v128
	global_load_dwordx4 v[18:21], v[18:19], off
	s_waitcnt lgkmcnt(0)
	s_barrier
	ds_read_b64_tr_b16 v[96:97], v158 offset:57408
	ds_read_b64_tr_b16 v[94:95], v158 offset:56320
	ds_read_b64_tr_b16 v[108:109], v157 offset:2112
	ds_read_b64_tr_b16 v[106:107], v157
	ds_read_b64_tr_b16 v[102:103], v157 offset:32
	ds_read_b64_tr_b16 v[104:105], v157 offset:2144
	s_waitcnt lgkmcnt(2)
	v_mfma_f32_16x16x32_bf16 v[70:73], v[94:97], v[106:109], v[70:73]
	ds_read_b64_tr_b16 v[168:169], v158 offset:65024
	ds_read_b64_tr_b16 v[170:171], v159 offset:57408
	ds_read_b64_tr_b16 v[98:99], v157 offset:16896
	s_cmp_eq_u32 s43, s83
	s_waitcnt lgkmcnt(3)
	v_mfma_f32_16x16x32_bf16 v[74:77], v[94:97], v[102:105], v[74:77]
	ds_read_b64_tr_b16 v[100:101], v157 offset:19008
	ds_read_b64_tr_b16 v[94:95], v157 offset:16928
	ds_read_b64_tr_b16 v[96:97], v157 offset:19040
	ds_read_b64_tr_b16 v[172:173], v158 offset:56352
	ds_read_b64_tr_b16 v[174:175], v158 offset:57440
	s_waitcnt lgkmcnt(4)
	v_mfma_f32_16x16x32_bf16 v[70:73], v[168:171], v[98:101], v[70:73]
	s_waitcnt lgkmcnt(2)
	v_mfma_f32_16x16x32_bf16 v[74:77], v[168:171], v[94:97], v[74:77]
	ds_read_b64_tr_b16 v[170:171], v159 offset:57440
	ds_read_b64_tr_b16 v[168:169], v158 offset:65056
	s_waitcnt lgkmcnt(2)
	v_mfma_f32_16x16x32_bf16 v[58:61], v[172:175], v[106:109], v[58:61]
	v_mfma_f32_16x16x32_bf16 v[82:85], v[172:175], v[102:105], v[82:85]
	s_waitcnt lgkmcnt(0)
	v_mfma_f32_16x16x32_bf16 v[58:61], v[168:171], v[98:101], v[58:61]
	v_mfma_f32_16x16x32_bf16 v[82:85], v[168:171], v[94:97], v[82:85]
	ds_read_b64_tr_b16 v[168:169], v158 offset:56384
	ds_read_b64_tr_b16 v[170:171], v158 offset:57472
	s_waitcnt lgkmcnt(0)
	v_mfma_f32_16x16x32_bf16 v[66:69], v[168:171], v[106:109], v[66:69]
	v_mfma_f32_16x16x32_bf16 v[78:81], v[168:171], v[102:105], v[78:81]
	ds_read_b64_tr_b16 v[168:169], v158 offset:65088
	ds_read_b64_tr_b16 v[170:171], v159 offset:57472
	s_waitcnt lgkmcnt(0)
	v_mfma_f32_16x16x32_bf16 v[66:69], v[168:171], v[98:101], v[66:69]
	v_mfma_f32_16x16x32_bf16 v[78:81], v[168:171], v[94:97], v[78:81]
	ds_read_b64_tr_b16 v[168:169], v158 offset:56416
	ds_read_b64_tr_b16 v[170:171], v158 offset:57504
	s_waitcnt lgkmcnt(0)
	v_mfma_f32_16x16x32_bf16 v[62:65], v[168:171], v[106:109], v[62:65]
	v_mfma_f32_16x16x32_bf16 v[86:89], v[168:171], v[102:105], v[86:89]
	ds_read_b64_tr_b16 v[168:169], v158 offset:65120
	ds_read_b64_tr_b16 v[170:171], v159 offset:57504
	s_waitcnt lgkmcnt(0)
	v_mfma_f32_16x16x32_bf16 v[62:65], v[168:171], v[98:101], v[62:65]
	v_mfma_f32_16x16x32_bf16 v[86:89], v[168:171], v[94:97], v[86:89]
	ds_read_b64_tr_b16 v[168:169], v158 offset:56448
	ds_read_b64_tr_b16 v[170:171], v158 offset:57536
	s_waitcnt lgkmcnt(0)
	v_mfma_f32_16x16x32_bf16 v[38:41], v[168:171], v[106:109], v[38:41]
	v_mfma_f32_16x16x32_bf16 v[50:53], v[168:171], v[102:105], v[50:53]
	ds_read_b64_tr_b16 v[168:169], v158 offset:65152
	ds_read_b64_tr_b16 v[170:171], v159 offset:57536
	s_waitcnt lgkmcnt(0)
	v_mfma_f32_16x16x32_bf16 v[38:41], v[168:171], v[98:101], v[38:41]
	v_mfma_f32_16x16x32_bf16 v[50:53], v[168:171], v[94:97], v[50:53]
	ds_read_b64_tr_b16 v[168:169], v158 offset:56480
	ds_read_b64_tr_b16 v[170:171], v158 offset:57568
	s_waitcnt lgkmcnt(0)
	v_mfma_f32_16x16x32_bf16 v[30:33], v[168:171], v[106:109], v[30:33]
	v_mfma_f32_16x16x32_bf16 v[54:57], v[168:171], v[102:105], v[54:57]
	ds_read_b64_tr_b16 v[168:169], v158 offset:65184
	ds_read_b64_tr_b16 v[170:171], v159 offset:57568
	s_waitcnt lgkmcnt(0)
	v_mfma_f32_16x16x32_bf16 v[30:33], v[168:171], v[98:101], v[30:33]
	v_mfma_f32_16x16x32_bf16 v[54:57], v[168:171], v[94:97], v[54:57]
	ds_read_b64_tr_b16 v[168:169], v158 offset:56512
	ds_read_b64_tr_b16 v[170:171], v158 offset:57600
	s_waitcnt lgkmcnt(0)
	v_mfma_f32_16x16x32_bf16 v[42:45], v[168:171], v[106:109], v[42:45]
	v_mfma_f32_16x16x32_bf16 v[46:49], v[168:171], v[102:105], v[46:49]
	ds_read_b64_tr_b16 v[168:169], v158 offset:65216
	ds_read_b64_tr_b16 v[170:171], v159 offset:57600
	s_waitcnt lgkmcnt(0)
	v_mfma_f32_16x16x32_bf16 v[42:45], v[168:171], v[98:101], v[42:45]
	v_mfma_f32_16x16x32_bf16 v[46:49], v[168:171], v[94:97], v[46:49]
	ds_read_b64_tr_b16 v[168:169], v158 offset:56544
	ds_read_b64_tr_b16 v[170:171], v158 offset:57632
	s_waitcnt lgkmcnt(0)
	v_mfma_f32_16x16x32_bf16 v[34:37], v[168:171], v[106:109], v[34:37]
	ds_read_b64_tr_b16 v[106:107], v158 offset:65248
	ds_read_b64_tr_b16 v[108:109], v159 offset:57632
	v_mfma_f32_16x16x32_bf16 v[102:105], v[168:171], v[102:105], v[26:29]
	ds_read_b128 v[168:171], v167 offset:4096
	s_waitcnt lgkmcnt(1)
	v_mfma_f32_16x16x32_bf16 v[26:29], v[106:109], v[98:101], v[34:37]
	s_waitcnt lgkmcnt(0)
	s_nop 1
	s_nop 0
	v_mov_b32_e32 v98, v168
	s_nop 0
	v_mov_b32_e32 v99, v169
	s_nop 0
	v_mov_b32_e32 v100, v170
	s_nop 0
	v_mov_b32_e32 v101, v171
	ds_read_b128 v[34:37], v167 offset:4160
	v_mfma_f32_16x16x32_bf16 v[94:97], v[106:109], v[94:97], v[102:105]
	v_mul_f32_e64 v70, v70, v98
	v_mul_f32_e64 v71, v71, v99
	v_pk_mul_f32 v[74:75], v[74:75], v[98:99]
	v_pk_mul_f32 v[72:73], v[72:73], v[100:101]
	s_waitcnt lgkmcnt(0)
	s_nop 0
	v_mov_b32_e32 v102, v34
	s_nop 0
	v_mov_b32_e32 v103, v35
	s_nop 0
	v_mov_b32_e32 v104, v36
	s_nop 0
	v_mov_b32_e32 v105, v37
	ds_read_b128 v[34:37], v167 offset:4224
	v_pk_mul_f32 v[76:77], v[76:77], v[100:101]
	v_pk_mul_f32 v[58:59], v[58:59], v[102:103]
	v_pk_mul_f32 v[82:83], v[82:83], v[102:103]
	v_pk_mul_f32 v[60:61], v[60:61], v[104:105]
	s_waitcnt lgkmcnt(0)
	s_nop 0
	v_mov_b32_e32 v98, v34
	s_nop 0
	v_mov_b32_e32 v99, v35
	s_nop 0
	v_mov_b32_e32 v100, v36
	s_nop 0
	v_mov_b32_e32 v101, v37
	ds_read_b128 v[34:37], v167 offset:4288
	v_pk_mul_f32 v[84:85], v[84:85], v[104:105]
	v_pk_mul_f32 v[66:67], v[66:67], v[98:99]
	v_pk_mul_f32 v[78:79], v[78:79], v[98:99]
	v_pk_mul_f32 v[68:69], v[68:69], v[100:101]
	s_waitcnt lgkmcnt(0)
	s_nop 0
	v_mov_b32_e32 v102, v34
	s_nop 0
	v_mov_b32_e32 v103, v35
	s_nop 0
	v_mov_b32_e32 v104, v36
	s_nop 0
	v_mov_b32_e32 v105, v37
	ds_read_b128 v[34:37], v167 offset:4352
	v_pk_mul_f32 v[80:81], v[80:81], v[100:101]
	v_pk_mul_f32 v[62:63], v[62:63], v[102:103]
	v_pk_mul_f32 v[86:87], v[86:87], v[102:103]
	v_pk_mul_f32 v[64:65], v[64:65], v[104:105]
	s_waitcnt lgkmcnt(0)
	s_nop 0
	v_mov_b32_e32 v98, v34
	s_nop 0
	v_mov_b32_e32 v99, v35
	s_nop 0
	v_mov_b32_e32 v100, v36
	s_nop 0
	v_mov_b32_e32 v101, v37
	ds_read_b128 v[34:37], v167 offset:4416
	v_pk_mul_f32 v[88:89], v[88:89], v[104:105]
	v_pk_mul_f32 v[38:39], v[38:39], v[98:99]
	v_pk_mul_f32 v[50:51], v[50:51], v[98:99]
	v_pk_mul_f32 v[40:41], v[40:41], v[100:101]
	s_waitcnt lgkmcnt(0)
	s_nop 0
	v_mov_b32_e32 v102, v34
	s_nop 0
	v_mov_b32_e32 v103, v35
	s_nop 0
	v_mov_b32_e32 v104, v36
	s_nop 0
	v_mov_b32_e32 v105, v37
	ds_read_b128 v[34:37], v167 offset:4480
	v_pk_mul_f32 v[52:53], v[52:53], v[100:101]
	v_pk_mul_f32 v[30:31], v[30:31], v[102:103]
	v_pk_mul_f32 v[54:55], v[54:55], v[102:103]
	v_pk_mul_f32 v[32:33], v[32:33], v[104:105]
	s_waitcnt lgkmcnt(0)
	s_nop 0
	v_mov_b32_e32 v98, v34
	s_nop 0
	v_mov_b32_e32 v99, v35
	s_nop 0
	v_mov_b32_e32 v100, v36
	s_nop 0
	v_mov_b32_e32 v101, v37
	ds_read_b128 v[34:37], v167 offset:4544
	v_pk_mul_f32 v[56:57], v[56:57], v[104:105]
	v_pk_mul_f32 v[42:43], v[42:43], v[98:99]
	v_pk_mul_f32 v[44:45], v[44:45], v[100:101]
	v_pk_mul_f32 v[48:49], v[48:49], v[100:101]
	s_waitcnt lgkmcnt(0)
	s_nop 0
	v_mov_b32_e32 v102, v34
	v_mov_b32_e32 v34, v35
	v_mov_b32_e32 v35, v36
	v_mov_b32_e32 v104, v35
	s_nop 0
	v_mov_b32_e32 v105, v37
	v_mov_b32_e32 v103, v34
	v_pk_mul_f32 v[46:47], v[46:47], v[98:99]
	v_pk_mul_f32 v[36:37], v[28:29], v[104:105]
	v_pk_mul_f32 v[34:35], v[26:27], v[102:103]
	v_pk_mul_f32 v[28:29], v[96:97], v[104:105]
	v_pk_mul_f32 v[26:27], v[94:95], v[102:103]
	s_cbranch_scc1 .LBB0_480
	.p2alignl 6, 3212836864

.LBB0_679:
	s_or_b64 exec, exec, s[62:63]
	s_waitcnt lgkmcnt(0)
	s_barrier
	ds_read_b128 v[136:139], v184
	ds_read_b128 v[142:145], v184 offset:16
	s_waitcnt vmcnt(8)
	v_lshlrev_b32_e32 v156, 16, v166
	v_and_b32_e32 v157, 0xffff0000, v166
	v_lshlrev_b32_e32 v166, 16, v167
	s_waitcnt lgkmcnt(1)
	v_mov_b32_e32 v81, v138
	v_lshlrev_b32_e32 v138, 16, v168
	v_mov_b32_e32 v80, v137
	v_mov_b32_e32 v137, v139
	v_and_b32_e32 v139, 0xffff0000, v168
	v_mul_f32_e32 v0, 0xbfb8aa3b, v138
	v_pk_add_f32 v[80:81], v[80:81], v[136:137]
	s_waitcnt lgkmcnt(0)
	v_mov_b32_e32 v136, v144
	v_exp_f32_e32 v0, v0
	v_mul_f32_e32 v144, 0xbfb8aa3b, v139
	v_exp_f32_e32 v144, v144
	v_mov_b32_e32 v137, v142
	v_mov_b32_e32 v142, v145
	v_add_f32_e32 v0, 1.0, v0
	v_pk_add_f32 v[146:147], v[136:137], v[142:143]
	v_rcp_f32_e32 v136, v0
	v_add_f32_e32 v0, 1.0, v144
	v_lshlrev_b32_e32 v142, 16, v169
	v_rcp_f32_e32 v137, v0
	v_and_b32_e32 v143, 0xffff0000, v169
	v_mul_f32_e32 v0, 0xbfb8aa3b, v142
	v_exp_f32_e32 v0, v0
	v_mul_f32_e32 v144, 0xbfb8aa3b, v143
	v_exp_f32_e32 v144, v144
	v_pk_mul_f32 v[148:149], v[136:137], v[138:139]
	v_add_f32_e32 v0, 1.0, v0
	v_rcp_f32_e32 v136, v0
	v_add_f32_e32 v0, 1.0, v144
	v_rcp_f32_e32 v137, v0
	v_mul_f32_e32 v0, 0xbfb8aa3b, v156
	v_exp_f32_e32 v0, v0
	v_mul_f32_e32 v138, 0xbfb8aa3b, v157
	v_exp_f32_e32 v138, v138
	v_and_b32_e32 v167, 0xffff0000, v167
	v_add_f32_e32 v0, 1.0, v0
	v_rcp_f32_e32 v224, v0
	v_add_f32_e32 v0, 1.0, v138
	v_rcp_f32_e32 v225, v0
	v_mul_f32_e32 v0, 0xbfb8aa3b, v166
	v_pk_mul_f32 v[168:169], v[136:137], v[142:143]
	v_exp_f32_e32 v0, v0
	v_mul_f32_e32 v136, 0xbfb8aa3b, v167
	v_exp_f32_e32 v142, v136
	ds_read_b128 v[136:139], v184 offset:512
	v_add_f32_e32 v0, 1.0, v0
	v_rcp_f32_e32 v226, v0
	v_add_f32_e32 v0, 1.0, v142
	ds_read_b128 v[142:145], v184 offset:528
	s_waitcnt lgkmcnt(1)
	v_mov_b32_e32 v228, v137
	v_mov_b32_e32 v229, v138
	v_mov_b32_e32 v137, v139
	v_pk_add_f32 v[136:137], v[228:229], v[136:137]
	s_waitcnt lgkmcnt(0)
	v_mov_b32_e32 v138, v144
	v_mov_b32_e32 v139, v142
	v_mov_b32_e32 v142, v145
	v_pk_add_f32 v[138:139], v[138:139], v[142:143]
	v_mov_b32_e32 v142, v136
	v_mov_b32_e32 v143, v80
	v_mov_b32_e32 v80, v137
	v_pk_add_f32 v[80:81], v[142:143], v[80:81]
	v_mov_b32_e32 v136, v139
	v_mov_b32_e32 v137, v147
	v_pk_add_f32 v[80:81], v[80:81], v[136:137]
	v_mov_b32_e32 v139, v146
	s_mov_b32 s62, 0x358637bd
	v_pk_add_f32 v[136:137], v[138:139], v[80:81]
	v_mov_b64_e32 v[80:81], s[62:63]
	v_pk_fma_f32 v[136:137], v[136:137], s[52:53], v[80:81] op_sel_hi:[1,0,0]
	v_rcp_f32_e32 v227, v0
	v_mul_f32_e32 v0, 0x4b800000, v137
	v_cmp_gt_f32_e32 vcc, s1, v137
	v_pk_mul_f32 v[142:143], v[224:225], v[156:157]
	v_pk_mul_f32 v[144:145], v[226:227], v[166:167]
	v_cndmask_b32_e32 v0, v137, v0, vcc
	v_rsq_f32_e32 v0, v0
	v_lshl_add_u64 v[138:139], s[56:57], 0, v[116:117]
	s_waitcnt vmcnt(4)
	v_lshlrev_b32_e32 v146, 16, v159
	v_and_b32_e32 v147, 0xffff0000, v159
	v_mul_f32_e32 v137, 0x45800000, v0
	v_cndmask_b32_e32 v0, v0, v137, vcc
	v_pk_mul_f32 v[106:107], v[106:107], v[0:1] op_sel_hi:[1,0]
	v_pk_mul_f32 v[108:109], v[108:109], v[0:1] op_sel_hi:[1,0]
	v_pk_mul_f32 v[102:103], v[102:103], v[0:1] op_sel_hi:[1,0]
	v_pk_mul_f32 v[104:105], v[104:105], v[0:1] op_sel_hi:[1,0]
	v_mul_f32_e32 v0, 0x4b800000, v136
	v_cmp_gt_f32_e32 vcc, s1, v136
	s_waitcnt vmcnt(0)
	v_pk_mul_f32 v[102:103], v[70:71], v[102:103]
	v_pk_mul_f32 v[104:105], v[72:73], v[104:105]
	v_cndmask_b32_e32 v0, v136, v0, vcc
	v_pk_mul_f32 v[102:103], v[142:143], v[102:103]
	v_pk_mul_f32 v[104:105], v[144:145], v[104:105]
	v_rsq_f32_e32 v0, v0
	v_cvt_pk_bf16_f32 v102, v102, v103
	v_cvt_pk_bf16_f32 v103, v104, v105
	global_store_dwordx2 v[138:139], v[102:103], off offset:32
	v_lshlrev_b32_e32 v102, 16, v164
	v_mul_f32_e32 v103, 0xbfb8aa3b, v102
	v_exp_f32_e32 v104, v103
	v_mul_f32_e32 v103, 0x45800000, v0
	v_cndmask_b32_e32 v0, v0, v103, vcc
	v_and_b32_e32 v103, 0xffff0000, v164
	v_mul_f32_e32 v105, 0xbfb8aa3b, v103
	v_exp_f32_e32 v105, v105
	v_pk_mul_f32 v[106:107], v[74:75], v[106:107]
	v_pk_mul_f32 v[108:109], v[76:77], v[108:109]
	v_pk_mul_f32 v[106:107], v[148:149], v[106:107]
	v_pk_mul_f32 v[108:109], v[168:169], v[108:109]
	v_cvt_pk_bf16_f32 v106, v106, v107
	v_cvt_pk_bf16_f32 v107, v108, v109
	v_lshlrev_b32_e32 v108, 16, v165
	v_and_b32_e32 v109, 0xffff0000, v165
	v_add_f32_e32 v104, 1.0, v104
	v_add_f32_e32 v105, 1.0, v105
	v_mul_f32_e32 v136, 0xbfb8aa3b, v108
	v_mul_f32_e32 v137, 0xbfb8aa3b, v109
	v_rcp_f32_e32 v104, v104
	v_rcp_f32_e32 v105, v105
	v_exp_f32_e32 v136, v136
	v_exp_f32_e32 v137, v137
	global_store_dwordx2 v[138:139], v[106:107], off
	v_pk_mul_f32 v[102:103], v[104:105], v[102:103]
	v_add_f32_e32 v104, 1.0, v136
	v_add_f32_e32 v105, 1.0, v137
	v_rcp_f32_e32 v104, v104
	v_rcp_f32_e32 v105, v105
	v_pk_mul_f32 v[106:107], v[152:153], v[0:1] op_sel_hi:[1,0]
	v_pk_mul_f32 v[100:101], v[100:101], v[0:1] op_sel_hi:[1,0]
	v_pk_mul_f32 v[106:107], v[74:75], v[106:107]
	v_pk_mul_f32 v[100:101], v[76:77], v[100:101]
	v_pk_mul_f32 v[104:105], v[104:105], v[108:109]
	v_pk_mul_f32 v[102:103], v[102:103], v[106:107]
	v_pk_mul_f32 v[100:101], v[104:105], v[100:101]
	v_cvt_pk_bf16_f32 v102, v102, v103
	v_cvt_pk_bf16_f32 v103, v100, v101
	v_lshlrev_b32_e32 v100, 16, v162
	v_mul_f32_e32 v101, 0xbfb8aa3b, v100
	v_exp_f32_e32 v106, v101
	v_lshl_add_u64 v[104:105], s[56:57], 0, v[120:121]
	v_and_b32_e32 v101, 0xffff0000, v162
	global_store_dwordx2 v[104:105], v[102:103], off
	v_mul_f32_e32 v103, 0xbfb8aa3b, v101
	v_exp_f32_e32 v103, v103
	v_lshlrev_b32_e32 v104, 16, v163
	v_and_b32_e32 v105, 0xffff0000, v163
	v_add_f32_e32 v102, 1.0, v106
	v_add_f32_e32 v103, 1.0, v103
	v_mul_f32_e32 v106, 0xbfb8aa3b, v104
	v_mul_f32_e32 v107, 0xbfb8aa3b, v105
	v_rcp_f32_e32 v102, v102
	v_rcp_f32_e32 v103, v103
	v_exp_f32_e32 v106, v106
	v_exp_f32_e32 v107, v107
	v_pk_mul_f32 v[98:99], v[98:99], v[0:1] op_sel_hi:[1,0]
	v_pk_mul_f32 v[100:101], v[102:103], v[100:101]
	v_add_f32_e32 v102, 1.0, v106
	v_add_f32_e32 v103, 1.0, v107
	v_rcp_f32_e32 v102, v102
	v_rcp_f32_e32 v103, v103
	v_pk_mul_f32 v[98:99], v[70:71], v[98:99]
	v_pk_mul_f32 v[96:97], v[96:97], v[0:1] op_sel_hi:[1,0]
	v_pk_mul_f32 v[98:99], v[100:101], v[98:99]
	v_pk_mul_f32 v[96:97], v[72:73], v[96:97]
	v_pk_mul_f32 v[100:101], v[102:103], v[104:105]
	v_cvt_pk_bf16_f32 v102, v98, v99
	v_pk_mul_f32 v[100:101], v[100:101], v[96:97]
	ds_read_b128 v[96:99], v184 offset:1024
	v_cvt_pk_bf16_f32 v103, v100, v101
	v_lshl_add_u64 v[100:101], s[56:57], 0, v[122:123]
	global_store_dwordx2 v[100:101], v[102:103], off
	ds_read_b128 v[100:103], v184 offset:1040
	s_waitcnt lgkmcnt(1)
	v_mov_b32_e32 v105, v98
	v_lshlrev_b32_e32 v98, 16, v160
	v_mov_b32_e32 v104, v97
	v_mov_b32_e32 v97, v99
	v_and_b32_e32 v99, 0xffff0000, v160
	v_mul_f32_e32 v0, 0xbfb8aa3b, v98
	v_pk_add_f32 v[104:105], v[104:105], v[96:97]
	v_exp_f32_e32 v0, v0
	v_mul_f32_e32 v97, 0xbfb8aa3b, v99
	s_waitcnt lgkmcnt(0)
	v_mov_b32_e32 v96, v102
	v_exp_f32_e32 v102, v97
	v_lshlrev_b32_e32 v108, 16, v161
	v_mov_b32_e32 v97, v100
	v_add_f32_e32 v0, 1.0, v0
	v_and_b32_e32 v109, 0xffff0000, v161
	v_mul_f32_e32 v100, 0xbfb8aa3b, v108
	v_rcp_f32_e32 v106, v0
	v_add_f32_e32 v0, 1.0, v102
	v_exp_f32_e32 v100, v100
	v_mul_f32_e32 v102, 0xbfb8aa3b, v109
	v_exp_f32_e32 v102, v102
	v_rcp_f32_e32 v107, v0
	v_add_f32_e32 v0, 1.0, v100
	v_rcp_f32_e32 v136, v0
	v_add_f32_e32 v0, 1.0, v102
	v_rcp_f32_e32 v137, v0
	v_mov_b32_e32 v100, v103
	v_pk_add_f32 v[138:139], v[96:97], v[100:101]
	v_pk_mul_f32 v[106:107], v[106:107], v[98:99]
	v_pk_mul_f32 v[108:109], v[136:137], v[108:109]
	v_lshlrev_b32_e32 v136, 16, v158
	v_and_b32_e32 v137, 0xffff0000, v158
	v_mul_f32_e32 v0, 0xbfb8aa3b, v136
	v_exp_f32_e32 v0, v0
	v_mul_f32_e32 v96, 0xbfb8aa3b, v137
	v_exp_f32_e32 v96, v96
	v_lshl_add_u64 v[142:143], s[56:57], 0, v[124:125]
	v_add_f32_e32 v0, 1.0, v0
	v_rcp_f32_e32 v144, v0
	v_add_f32_e32 v0, 1.0, v96
	v_rcp_f32_e32 v145, v0
	v_mul_f32_e32 v0, 0xbfb8aa3b, v146
	v_exp_f32_e32 v0, v0
	v_mul_f32_e32 v96, 0xbfb8aa3b, v147
	v_exp_f32_e32 v100, v96
	ds_read_b128 v[96:99], v184 offset:1536
	v_add_f32_e32 v0, 1.0, v0
	v_rcp_f32_e32 v148, v0
	v_add_f32_e32 v0, 1.0, v100
	ds_read_b128 v[100:103], v184 offset:1552
	s_waitcnt lgkmcnt(1)
	v_mov_b32_e32 v152, v97
	v_mov_b32_e32 v153, v98
	v_mov_b32_e32 v97, v99
	v_pk_add_f32 v[96:97], v[152:153], v[96:97]
	s_waitcnt lgkmcnt(0)
	v_mov_b32_e32 v98, v102
	v_mov_b32_e32 v99, v100
	v_mov_b32_e32 v100, v103
	v_pk_add_f32 v[98:99], v[98:99], v[100:101]
	v_mov_b32_e32 v100, v96
	v_mov_b32_e32 v101, v104
	v_mov_b32_e32 v104, v97
	v_pk_add_f32 v[96:97], v[100:101], v[104:105]
	v_mov_b32_e32 v100, v99
	v_mov_b32_e32 v101, v139
	v_pk_add_f32 v[96:97], v[96:97], v[100:101]
	v_mov_b32_e32 v99, v138
	v_pk_add_f32 v[96:97], v[98:99], v[96:97]
	v_rcp_f32_e32 v149, v0
	v_pk_fma_f32 v[80:81], v[96:97], s[52:53], v[80:81] op_sel_hi:[1,0,0]
	v_pk_mul_f32 v[96:97], v[144:145], v[136:137]
	v_mul_f32_e32 v0, 0x4b800000, v81
	v_cmp_gt_f32_e32 vcc, s1, v81
	v_pk_mul_f32 v[152:153], v[148:149], v[146:147]
	v_lshl_add_u64 v[168:169], s[56:57], 0, v[126:127]
	v_cndmask_b32_e32 v0, v81, v0, vcc
	v_rsq_f32_e32 v0, v0
	s_add_i32 s75, s75, 1
	s_add_u32 s60, s60, 0xfffa0000
	s_addc_u32 s61, s61, -1
	v_mul_f32_e32 v81, 0x45800000, v0
	v_cndmask_b32_e32 v0, v0, v81, vcc
	v_pk_mul_f32 v[90:91], v[90:91], v[0:1] op_sel_hi:[1,0]
	v_pk_mul_f32 v[94:95], v[94:95], v[0:1] op_sel_hi:[1,0]
	v_pk_mul_f32 v[90:91], v[74:75], v[90:91]
	v_pk_mul_f32 v[94:95], v[76:77], v[94:95]
	v_pk_mul_f32 v[90:91], v[106:107], v[90:91]
	v_pk_mul_f32 v[94:95], v[108:109], v[94:95]
	v_cvt_pk_bf16_f32 v90, v90, v91
	v_cvt_pk_bf16_f32 v91, v94, v95
	global_store_dwordx2 v[142:143], v[90:91], off
	v_pk_mul_f32 v[90:91], v[92:93], v[0:1] op_sel_hi:[1,0]
	v_pk_mul_f32 v[88:89], v[88:89], v[0:1] op_sel_hi:[1,0]
	v_mul_f32_e32 v0, 0x4b800000, v80
	v_cmp_gt_f32_e32 vcc, s1, v80
	v_pk_mul_f32 v[90:91], v[70:71], v[90:91]
	v_pk_mul_f32 v[224:225], v[72:73], v[88:89]
	v_cndmask_b32_e32 v0, v80, v0, vcc
	v_pk_mul_f32 v[108:109], v[96:97], v[90:91]
	ds_read_b64_tr_b16 v[90:91], v213 offset:57408
	ds_read_b64_tr_b16 v[88:89], v213 offset:56320
	ds_read_b64_tr_b16 v[94:95], v210 offset:2112
	ds_read_b64_tr_b16 v[92:93], v210
	ds_read_b64_tr_b16 v[98:99], v210 offset:2144
	ds_read_b64_tr_b16 v[96:97], v210 offset:32
	ds_read_b64_tr_b16 v[100:101], v213 offset:56352
	ds_read_b64_tr_b16 v[104:105], v213 offset:56384
	ds_read_b64_tr_b16 v[136:137], v213 offset:56416
	ds_read_b64_tr_b16 v[102:103], v213 offset:57440
	ds_read_b64_tr_b16 v[106:107], v213 offset:57472
	ds_read_b64_tr_b16 v[138:139], v213 offset:57504
	v_rsq_f32_e32 v0, v0
	ds_read_b64_tr_b16 v[142:143], v213 offset:65024
	ds_read_b64_tr_b16 v[144:145], v214 offset:57408
	ds_read_b64_tr_b16 v[146:147], v210 offset:16896
	ds_read_b64_tr_b16 v[148:149], v210 offset:19008
	ds_read_b64_tr_b16 v[158:159], v210 offset:19040
	ds_read_b64_tr_b16 v[156:157], v210 offset:16928
	s_waitcnt lgkmcnt(8)
	v_mfma_f32_16x16x32_bf16 v[10:13], v[100:103], v[92:95], v[10:13]
	v_and_b32_e32 v81, 0xffff0000, v150
	v_mul_f32_e32 v80, 0x45800000, v0
	v_cndmask_b32_e32 v0, v0, v80, vcc
	v_mfma_f32_16x16x32_bf16 v[18:21], v[100:103], v[96:99], v[18:21]
	v_lshlrev_b32_e32 v80, 16, v150
	v_mul_f32_e32 v100, 0xbfb8aa3b, v80
	v_mul_f32_e32 v101, 0xbfb8aa3b, v81
	v_mfma_f32_16x16x32_bf16 v[30:33], v[88:91], v[92:95], v[30:33]
	v_exp_f32_e32 v100, v100
	v_pk_mul_f32 v[86:87], v[86:87], v[0:1] op_sel_hi:[1,0]
	v_pk_mul_f32 v[152:153], v[152:153], v[224:225]
	v_mfma_f32_16x16x32_bf16 v[6:9], v[88:91], v[96:99], v[6:9]
	ds_read_b64_tr_b16 v[88:89], v213 offset:65056
	ds_read_b64_tr_b16 v[160:161], v213 offset:65088
	ds_read_b64_tr_b16 v[164:165], v213 offset:65120
	ds_read_b64_tr_b16 v[90:91], v214 offset:57440
	ds_read_b64_tr_b16 v[162:163], v214 offset:57472
	ds_read_b64_tr_b16 v[166:167], v214 offset:57504
	v_pk_mul_f32 v[74:75], v[74:75], v[86:87]
	v_lshlrev_b32_e32 v86, 16, v151
	s_waitcnt lgkmcnt(2)
	v_mfma_f32_16x16x32_bf16 v[10:13], v[88:91], v[146:149], v[10:13]
	v_mul_f32_e32 v87, 0xbfb8aa3b, v86
	v_cvt_pk_bf16_f32 v108, v108, v109
	v_cvt_pk_bf16_f32 v109, v152, v153
	v_mfma_f32_16x16x32_bf16 v[18:21], v[88:91], v[156:159], v[18:21]
	v_exp_f32_e32 v89, v101
	v_add_f32_e32 v88, 1.0, v100
	v_rcp_f32_e32 v88, v88
	global_store_dwordx2 v[168:169], v[108:109], off
	v_add_f32_e32 v89, 1.0, v89
	v_rcp_f32_e32 v89, v89
	v_mfma_f32_16x16x32_bf16 v[14:17], v[104:107], v[92:95], v[14:17]
	v_mul_f32_e64 v82, v82, v0
	v_mul_f32_e64 v83, v83, v0
	v_pk_mul_f32 v[78:79], v[78:79], v[0:1] op_sel_hi:[1,0]
	v_pk_mul_f32 v[80:81], v[88:89], v[80:81]
	v_exp_f32_e32 v88, v87
	v_pk_mul_f32 v[80:81], v[80:81], v[74:75]
	v_and_b32_e32 v87, 0xffff0000, v151
	v_mfma_f32_16x16x32_bf16 v[26:29], v[104:107], v[96:99], v[26:29]
	v_add_f32_e32 v74, 1.0, v88
	v_rcp_f32_e32 v88, v74
	v_mul_f32_e32 v74, 0xbfb8aa3b, v87
	v_exp_f32_e32 v89, v74
	v_pk_mul_f32 v[74:75], v[84:85], v[0:1] op_sel_hi:[1,0]
	v_mfma_f32_16x16x32_bf16 v[38:41], v[136:139], v[92:95], v[38:41]
	v_mul_f32_e64 v108, v76, v74
	v_mul_f32_e64 v109, v77, v75
	v_add_f32_e32 v74, 1.0, v89
	v_rcp_f32_e32 v89, v74
	ds_read_b64_tr_b16 v[74:75], v213 offset:56448
	ds_read_b64_tr_b16 v[76:77], v213 offset:57536
	v_mfma_f32_16x16x32_bf16 v[50:53], v[136:139], v[96:99], v[50:53]
	v_cvt_pk_bf16_f32 v80, v80, v81
	v_pk_mul_f32 v[136:137], v[88:89], v[86:87]
	ds_read_b64_tr_b16 v[84:85], v213 offset:56480
	ds_read_b64_tr_b16 v[88:89], v213 offset:56512
	ds_read_b64_tr_b16 v[100:101], v213 offset:56544
	ds_read_b64_tr_b16 v[86:87], v213 offset:57568
	ds_read_b64_tr_b16 v[90:91], v213 offset:57600
	ds_read_b64_tr_b16 v[102:103], v213 offset:57632
	ds_read_b64_tr_b16 v[104:105], v213 offset:65152
	ds_read_b64_tr_b16 v[106:107], v214 offset:57536
	s_waitcnt lgkmcnt(8)
	v_mfma_f32_16x16x32_bf16 v[22:25], v[74:77], v[92:95], v[22:25]
	v_mul_f32_e64 v108, v136, v108
	v_mul_f32_e64 v109, v137, v109
	v_pk_mul_f32 v[70:71], v[70:71], v[82:83]
	v_cvt_pk_bf16_f32 v81, v108, v109
	v_mfma_f32_16x16x32_bf16 v[34:37], v[74:77], v[96:99], v[34:37]
	v_lshl_add_u64 v[108:109], s[56:57], 0, v[128:129]
	v_pk_mul_f32 v[72:73], v[72:73], v[78:79]
	v_lshl_add_u32 v0, s67, 9, v179
	v_mfma_f32_16x16x32_bf16 v[30:33], v[142:145], v[146:149], v[30:33]
	s_sub_i32 s54, s54, 64
	v_mfma_f32_16x16x32_bf16 v[6:9], v[142:145], v[156:159], v[6:9]
	ds_read_b64_tr_b16 v[74:75], v213 offset:65184
	ds_read_b64_tr_b16 v[136:137], v213 offset:65216
	ds_read_b64_tr_b16 v[142:143], v213 offset:65248
	ds_read_b64_tr_b16 v[76:77], v214 offset:57568
	ds_read_b64_tr_b16 v[138:139], v214 offset:57600
	ds_read_b64_tr_b16 v[144:145], v214 offset:57632
	global_store_dwordx2 v[108:109], v[80:81], off
	v_lshlrev_b32_e32 v80, 16, v140
	v_and_b32_e32 v81, 0xffff0000, v140
	s_waitcnt lgkmcnt(6)
	v_mfma_f32_16x16x32_bf16 v[22:25], v[104:107], v[146:149], v[22:25]
	v_mfma_f32_16x16x32_bf16 v[34:37], v[104:107], v[156:159], v[34:37]
	v_mul_f32_e32 v104, 0xbfb8aa3b, v80
	v_mul_f32_e32 v105, 0xbfb8aa3b, v81
	v_exp_f32_e32 v104, v104
	v_mfma_f32_16x16x32_bf16 v[42:45], v[84:87], v[92:95], v[42:45]
	v_mfma_f32_16x16x32_bf16 v[54:57], v[84:87], v[96:99], v[54:57]
	v_exp_f32_e32 v85, v105
	v_add_f32_e32 v84, 1.0, v104
	v_rcp_f32_e32 v84, v84
	s_waitcnt lgkmcnt(2)
	v_mfma_f32_16x16x32_bf16 v[42:45], v[74:77], v[146:149], v[42:45]
	v_add_f32_e32 v85, 1.0, v85
	v_rcp_f32_e32 v85, v85
	v_mfma_f32_16x16x32_bf16 v[54:57], v[74:77], v[156:159], v[54:57]
	v_mul_f32_e64 v74, v84, v80
	v_mul_f32_e64 v75, v85, v81
	v_pk_mul_f32 v[70:71], v[74:75], v[70:71]
	v_lshlrev_b32_e32 v74, 16, v141
	v_and_b32_e32 v75, 0xffff0000, v141
	v_mul_f32_e32 v76, 0xbfb8aa3b, v74
	v_mul_f32_e32 v77, 0xbfb8aa3b, v75
	v_exp_f32_e32 v76, v76
	v_exp_f32_e32 v77, v77
	v_cvt_pk_bf16_f32 v78, v70, v71
	v_lshl_add_u64 v[80:81], s[56:57], 0, v[130:131]
	v_add_f32_e32 v76, 1.0, v76
	v_add_f32_e32 v77, 1.0, v77
	v_rcp_f32_e32 v76, v76
	v_rcp_f32_e32 v77, v77
	v_mfma_f32_16x16x32_bf16 v[14:17], v[160:163], v[146:149], v[14:17]
	s_add_u32 s56, s56, 0xfffe0000
	s_addc_u32 s57, s57, -1
	v_pk_mul_f32 v[74:75], v[76:77], v[74:75]
	v_mfma_f32_16x16x32_bf16 v[26:29], v[160:163], v[156:159], v[26:29]
	v_mul_f32_e64 v74, v74, v72
	v_mul_f32_e64 v75, v75, v73
	ds_read_b128 v[70:73], v0 offset:4096
	v_cvt_pk_bf16_f32 v79, v74, v75
	ds_read_b128 v[74:77], v0 offset:4160
	global_store_dwordx2 v[80:81], v[78:79], off
	v_mfma_f32_16x16x32_bf16 v[38:41], v[164:167], v[146:149], v[38:41]
	s_waitcnt lgkmcnt(1)
	s_nop 0
	v_mov_b32_e32 v82, v70
	v_mov_b32_e32 v83, v71
	v_mov_b32_e32 v70, v72
	v_mov_b32_e32 v71, v73
	s_nop 0
	s_nop 0
	s_nop 0
	v_mfma_f32_16x16x32_bf16 v[50:53], v[164:167], v[156:159], v[50:53]
	s_add_u32 s58, s58, 0xfffe0000
	v_pk_mul_f32 v[32:33], v[32:33], v[70:71]
	v_pk_mul_f32 v[8:9], v[8:9], v[70:71]
	s_waitcnt lgkmcnt(0)
	v_mov_b32_e32 v70, v74
	v_mov_b32_e32 v71, v76
	v_mov_b32_e32 v78, v70
	v_mov_b32_e32 v70, v75
	v_mov_b32_e32 v80, v71
	s_nop 0
	v_mov_b32_e32 v81, v77
	v_mov_b32_e32 v79, v70
	ds_read_b128 v[70:73], v0 offset:4224
	ds_read_b128 v[74:77], v0 offset:4288
	v_pk_mul_f32 v[30:31], v[30:31], v[82:83]
	v_pk_mul_f32 v[6:7], v[6:7], v[82:83]
	v_pk_mul_f32 v[12:13], v[12:13], v[80:81]
	s_waitcnt lgkmcnt(1)
	s_nop 0
	v_mov_b32_e32 v82, v70
	v_mov_b32_e32 v83, v71
	v_mov_b32_e32 v70, v72
	v_mov_b32_e32 v71, v73
	s_nop 0
	s_nop 0
	v_pk_mul_f32 v[10:11], v[10:11], v[78:79]
	v_pk_mul_f32 v[20:21], v[20:21], v[80:81]
	v_pk_mul_f32 v[18:19], v[18:19], v[78:79]
	v_pk_mul_f32 v[16:17], v[16:17], v[70:71]
	v_pk_mul_f32 v[28:29], v[28:29], v[70:71]
	s_waitcnt lgkmcnt(0)
	v_mov_b32_e32 v70, v74
	v_mov_b32_e32 v71, v76
	v_mov_b32_e32 v78, v70
	v_mov_b32_e32 v70, v75
	v_mov_b32_e32 v80, v71
	s_nop 0
	v_mov_b32_e32 v81, v77
	v_mov_b32_e32 v79, v70
	ds_read_b128 v[70:73], v0 offset:4352
	ds_read_b128 v[74:77], v0 offset:4416
	s_nop 0
	v_pk_mul_f32 v[40:41], v[40:41], v[80:81]
	v_pk_mul_f32 v[38:39], v[38:39], v[78:79]
	s_waitcnt lgkmcnt(1)
	s_nop 0
	v_pk_mul_f32 v[14:15], v[14:15], v[82:83]
	v_pk_mul_f32 v[26:27], v[26:27], v[82:83]
	v_mov_b32_e32 v82, v70
	v_mov_b32_e32 v83, v71
	v_mov_b32_e32 v70, v72
	v_mov_b32_e32 v71, v73
	s_nop 0
	s_nop 0
	v_pk_mul_f32 v[52:53], v[52:53], v[80:81]
	v_pk_mul_f32 v[50:51], v[50:51], v[78:79]
	v_mfma_f32_16x16x32_bf16 v[46:49], v[88:91], v[92:95], v[46:49]
	v_mul_f32_e64 v24, v24, v70
	v_mul_f32_e64 v25, v25, v71
	v_pk_mul_f32 v[36:37], v[36:37], v[70:71]
	s_waitcnt lgkmcnt(0)
	v_mov_b32_e32 v70, v74
	v_mov_b32_e32 v71, v76
	v_mov_b32_e32 v78, v70
	v_mov_b32_e32 v70, v75
	v_mov_b32_e32 v80, v71
	s_nop 0
	v_mov_b32_e32 v81, v77
	v_mov_b32_e32 v79, v70
	ds_read_b128 v[70:73], v0 offset:4480
	ds_read_b128 v[74:77], v0 offset:4544
	v_mfma_f32_16x16x32_bf16 v[62:65], v[88:91], v[96:99], v[62:65]
	s_nop 0
	s_addc_u32 s59, s59, -1
	s_waitcnt lgkmcnt(1)
	s_nop 0
	v_mov_b32_e32 v70, v70
	v_mov_b32_e32 v0, v71
	v_mov_b32_e32 v71, v72
	v_mfma_f32_16x16x32_bf16 v[58:61], v[100:103], v[92:95], v[58:61]
	v_mov_b32_e32 v72, v71
	s_nop 0
	v_mov_b32_e32 v73, v73
	v_mfma_f32_16x16x32_bf16 v[66:69], v[100:103], v[96:99], v[66:69]
	v_mov_b32_e32 v71, v0
	s_waitcnt lgkmcnt(0)
	s_nop 0
	v_mov_b32_e32 v74, v74
	v_mov_b32_e32 v0, v75
	v_mov_b32_e32 v75, v76
	v_mov_b32_e32 v76, v75
	v_mov_b32_e32 v75, v77
	v_mfma_f32_16x16x32_bf16 v[46:49], v[136:139], v[146:149], v[46:49]
	v_mov_b32_e32 v77, v75
	v_mov_b32_e32 v75, v0
	v_pk_mul_f32 v[22:23], v[22:23], v[82:83]
	v_mfma_f32_16x16x32_bf16 v[62:65], v[136:139], v[156:159], v[62:65]
	v_mul_f32_e64 v34, v34, v82
	v_mul_f32_e64 v35, v35, v83
	v_pk_mul_f32 v[44:45], v[44:45], v[80:81]
	v_pk_mul_f32 v[42:43], v[42:43], v[78:79]
	v_mfma_f32_16x16x32_bf16 v[58:61], v[142:145], v[146:149], v[58:61]
	v_mul_f32_e64 v56, v56, v80
	v_mul_f32_e64 v57, v57, v81
	v_pk_mul_f32 v[54:55], v[54:55], v[78:79]
	v_pk_mul_f32 v[48:49], v[48:49], v[72:73]
	v_mfma_f32_16x16x32_bf16 v[66:69], v[142:145], v[156:159], v[66:69]
	v_mul_f32_e64 v46, v46, v70
	v_mul_f32_e64 v47, v47, v71
	v_pk_mul_f32 v[64:65], v[64:65], v[72:73]
	v_pk_mul_f32 v[62:63], v[62:63], v[70:71]
	v_pk_mul_f32 v[60:61], v[60:61], v[76:77]
	v_pk_mul_f32 v[58:59], v[58:59], v[74:75]
	s_nop 1
	v_pk_mul_f32 v[68:69], v[68:69], v[76:77]
	s_cmp_lg_u32 s75, 8
	v_pk_mul_f32 v[66:67], v[66:67], v[74:75]
	s_cbranch_scc0 .LBB0_654
	.p2alignl 6, 3212836864

.LBB0_761:
	s_ashr_i32 s13, s12, 31
	s_lshl_b64 s[20:21], s[12:13], 19
	s_add_u32 s20, s30, s20
	s_addc_u32 s21, s31, s21
	s_and_b64 s[22:23], s[2:3], exec
	s_cselect_b32 s13, s21, s25
	s_cselect_b32 s49, s20, s24
	s_ashr_i32 s15, s14, 31
	s_lshl_b64 s[22:23], s[14:15], 19
	s_add_u32 s22, s34, s22
	s_addc_u32 s23, s35, s23
	s_and_b64 s[28:29], s[2:3], exec
	s_cselect_b32 s15, s23, s27
	s_cselect_b32 s50, s22, s26
	s_add_u32 s24, s24, 0x40080
	s_addc_u32 s25, s25, 0
	s_add_u32 s51, s26, 0x100
	v_mov_b32_e32 v0, 0
	s_addc_u32 s52, s27, 0
	s_mov_b32 s53, -2
	v_mov_b32_e32 v1, v0
	v_mov_b32_e32 v2, v0
	v_mov_b32_e32 v3, v0
	v_mov_b32_e32 v4, v0
	v_mov_b32_e32 v5, v0
	v_mov_b32_e32 v6, v0
	v_mov_b32_e32 v7, v0
	v_mov_b32_e32 v8, v0
	v_mov_b32_e32 v9, v0
	v_mov_b32_e32 v10, v0
	v_mov_b32_e32 v11, v0
	v_mov_b32_e32 v12, v0
	v_mov_b32_e32 v13, v0
	v_mov_b32_e32 v14, v0
	v_mov_b32_e32 v15, v0
	v_mov_b32_e32 v24, v0
	v_mov_b32_e32 v25, v0
	v_mov_b32_e32 v26, v0
	v_mov_b32_e32 v27, v0
	v_mov_b32_e32 v28, v0
	v_mov_b32_e32 v29, v0
	v_mov_b32_e32 v30, v0
	v_mov_b32_e32 v31, v0
	v_mov_b32_e32 v40, v0
	v_mov_b32_e32 v41, v0
	v_mov_b32_e32 v42, v0
	v_mov_b32_e32 v43, v0
	v_mov_b32_e32 v44, v0
	v_mov_b32_e32 v45, v0
	v_mov_b32_e32 v46, v0
	v_mov_b32_e32 v47, v0
	v_mov_b32_e32 v16, v0
	v_mov_b32_e32 v17, v0
	v_mov_b32_e32 v18, v0
	v_mov_b32_e32 v19, v0
	v_mov_b32_e32 v20, v0
	v_mov_b32_e32 v21, v0
	v_mov_b32_e32 v22, v0
	v_mov_b32_e32 v23, v0
	v_mov_b32_e32 v32, v0
	v_mov_b32_e32 v33, v0
	v_mov_b32_e32 v34, v0
	v_mov_b32_e32 v35, v0
	v_mov_b32_e32 v36, v0
	v_mov_b32_e32 v37, v0
	v_mov_b32_e32 v38, v0
	v_mov_b32_e32 v39, v0
	v_mov_b32_e32 v48, v0
	v_mov_b32_e32 v49, v0
	v_mov_b32_e32 v50, v0
	v_mov_b32_e32 v51, v0
	v_mov_b32_e32 v52, v0
	v_mov_b32_e32 v53, v0
	v_mov_b32_e32 v54, v0
	v_mov_b32_e32 v55, v0
	v_mov_b32_e32 v56, v0
	v_mov_b32_e32 v57, v0
	v_mov_b32_e32 v58, v0
	v_mov_b32_e32 v59, v0
	v_mov_b32_e32 v60, v0
	v_mov_b32_e32 v61, v0
	v_mov_b32_e32 v62, v0
	v_mov_b32_e32 v63, v0
	v_mov_b32_e32 v64, v0
	v_mov_b32_e32 v65, v0
	v_mov_b32_e32 v66, v0
	v_mov_b32_e32 v67, v0
	v_mov_b32_e32 v68, v0
	v_mov_b32_e32 v69, v0
	v_mov_b32_e32 v70, v0
	v_mov_b32_e32 v71, v0
	v_mov_b32_e32 v72, v0
	v_mov_b32_e32 v73, v0
	v_mov_b32_e32 v74, v0
	v_mov_b32_e32 v75, v0
	v_mov_b32_e32 v76, v0
	v_mov_b32_e32 v77, v0
	v_mov_b32_e32 v78, v0
	v_mov_b32_e32 v79, v0
	v_mov_b32_e32 v88, v0
	v_mov_b32_e32 v89, v0
	v_mov_b32_e32 v90, v0
	v_mov_b32_e32 v91, v0
	v_mov_b32_e32 v92, v0
	v_mov_b32_e32 v93, v0
	v_mov_b32_e32 v94, v0
	v_mov_b32_e32 v95, v0
	v_mov_b32_e32 v104, v0
	v_mov_b32_e32 v105, v0
	v_mov_b32_e32 v106, v0
	v_mov_b32_e32 v107, v0
	v_mov_b32_e32 v108, v0
	v_mov_b32_e32 v109, v0
	v_mov_b32_e32 v110, v0
	v_mov_b32_e32 v111, v0
	v_mov_b32_e32 v80, v0
	v_mov_b32_e32 v81, v0
	v_mov_b32_e32 v82, v0
	v_mov_b32_e32 v83, v0
	v_mov_b32_e32 v84, v0
	v_mov_b32_e32 v85, v0
	v_mov_b32_e32 v86, v0
	v_mov_b32_e32 v87, v0
	v_mov_b32_e32 v96, v0
	v_mov_b32_e32 v97, v0
	v_mov_b32_e32 v98, v0
	v_mov_b32_e32 v99, v0
	v_mov_b32_e32 v100, v0
	v_mov_b32_e32 v101, v0
	v_mov_b32_e32 v102, v0
	v_mov_b32_e32 v103, v0
	v_mov_b32_e32 v112, v0
	v_mov_b32_e32 v113, v0
	v_mov_b32_e32 v114, v0
	v_mov_b32_e32 v115, v0
	v_mov_b32_e32 v116, v0
	v_mov_b32_e32 v117, v0
	v_mov_b32_e32 v118, v0
	v_mov_b32_e32 v119, v0
	v_mov_b32_e32 v120, v0
	v_mov_b32_e32 v121, v0
	v_mov_b32_e32 v122, v0
	v_mov_b32_e32 v123, v0
	v_mov_b32_e32 v124, v0
	v_mov_b32_e32 v125, v0
	v_mov_b32_e32 v126, v0
	v_mov_b32_e32 v127, v0
	.p2alignl 6, 3212836864

.LBB0_841:
	s_ashr_i32 s23, s22, 31
	s_lshl_b64 s[34:35], s[22:23], 19
	s_add_u32 s34, s46, s34
	s_addc_u32 s35, s47, s35
	s_and_b64 s[36:37], s[30:31], exec
	s_cselect_b32 s23, s35, s39
	s_cselect_b32 s27, s34, s38
	s_ashr_i32 s25, s24, 31
	s_lshl_b64 s[36:37], s[24:25], 19
	s_add_u32 s36, s48, s36
	s_addc_u32 s37, s49, s37
	s_and_b64 s[42:43], s[30:31], exec
	s_cselect_b32 s25, s37, s41
	s_cselect_b32 s61, s36, s40
	s_add_u32 s38, s38, 0x40080
	s_addc_u32 s39, s39, 0
	s_add_u32 s62, s40, 0x100
	v_mov_b32_e32 v0, 0
	s_addc_u32 s63, s41, 0
	s_mov_b32 s64, -2
	v_mov_b32_e32 v1, v0
	v_mov_b32_e32 v2, v0
	v_mov_b32_e32 v3, v0
	v_mov_b32_e32 v4, v0
	v_mov_b32_e32 v5, v0
	v_mov_b32_e32 v6, v0
	v_mov_b32_e32 v7, v0
	v_mov_b32_e32 v8, v0
	v_mov_b32_e32 v9, v0
	v_mov_b32_e32 v10, v0
	v_mov_b32_e32 v11, v0
	v_mov_b32_e32 v12, v0
	v_mov_b32_e32 v13, v0
	v_mov_b32_e32 v14, v0
	v_mov_b32_e32 v15, v0
	v_mov_b32_e32 v24, v0
	v_mov_b32_e32 v25, v0
	v_mov_b32_e32 v26, v0
	v_mov_b32_e32 v27, v0
	v_mov_b32_e32 v28, v0
	v_mov_b32_e32 v29, v0
	v_mov_b32_e32 v30, v0
	v_mov_b32_e32 v31, v0
	v_mov_b32_e32 v40, v0
	v_mov_b32_e32 v41, v0
	v_mov_b32_e32 v42, v0
	v_mov_b32_e32 v43, v0
	v_mov_b32_e32 v44, v0
	v_mov_b32_e32 v45, v0
	v_mov_b32_e32 v46, v0
	v_mov_b32_e32 v47, v0
	v_mov_b32_e32 v16, v0
	v_mov_b32_e32 v17, v0
	v_mov_b32_e32 v18, v0
	v_mov_b32_e32 v19, v0
	v_mov_b32_e32 v20, v0
	v_mov_b32_e32 v21, v0
	v_mov_b32_e32 v22, v0
	v_mov_b32_e32 v23, v0
	v_mov_b32_e32 v32, v0
	v_mov_b32_e32 v33, v0
	v_mov_b32_e32 v34, v0
	v_mov_b32_e32 v35, v0
	v_mov_b32_e32 v36, v0
	v_mov_b32_e32 v37, v0
	v_mov_b32_e32 v38, v0
	v_mov_b32_e32 v39, v0
	v_mov_b32_e32 v48, v0
	v_mov_b32_e32 v49, v0
	v_mov_b32_e32 v50, v0
	v_mov_b32_e32 v51, v0
	v_mov_b32_e32 v52, v0
	v_mov_b32_e32 v53, v0
	v_mov_b32_e32 v54, v0
	v_mov_b32_e32 v55, v0
	v_mov_b32_e32 v56, v0
	v_mov_b32_e32 v57, v0
	v_mov_b32_e32 v58, v0
	v_mov_b32_e32 v59, v0
	v_mov_b32_e32 v60, v0
	v_mov_b32_e32 v61, v0
	v_mov_b32_e32 v62, v0
	v_mov_b32_e32 v63, v0
	v_mov_b32_e32 v64, v0
	v_mov_b32_e32 v65, v0
	v_mov_b32_e32 v66, v0
	v_mov_b32_e32 v67, v0
	v_mov_b32_e32 v68, v0
	v_mov_b32_e32 v69, v0
	v_mov_b32_e32 v70, v0
	v_mov_b32_e32 v71, v0
	v_mov_b32_e32 v72, v0
	v_mov_b32_e32 v73, v0
	v_mov_b32_e32 v74, v0
	v_mov_b32_e32 v75, v0
	v_mov_b32_e32 v76, v0
	v_mov_b32_e32 v77, v0
	v_mov_b32_e32 v78, v0
	v_mov_b32_e32 v79, v0
	v_mov_b32_e32 v88, v0
	v_mov_b32_e32 v89, v0
	v_mov_b32_e32 v90, v0
	v_mov_b32_e32 v91, v0
	v_mov_b32_e32 v92, v0
	v_mov_b32_e32 v93, v0
	v_mov_b32_e32 v94, v0
	v_mov_b32_e32 v95, v0
	v_mov_b32_e32 v104, v0
	v_mov_b32_e32 v105, v0
	v_mov_b32_e32 v106, v0
	v_mov_b32_e32 v107, v0
	v_mov_b32_e32 v108, v0
	v_mov_b32_e32 v109, v0
	v_mov_b32_e32 v110, v0
	v_mov_b32_e32 v111, v0
	v_mov_b32_e32 v80, v0
	v_mov_b32_e32 v81, v0
	v_mov_b32_e32 v82, v0
	v_mov_b32_e32 v83, v0
	v_mov_b32_e32 v84, v0
	v_mov_b32_e32 v85, v0
	v_mov_b32_e32 v86, v0
	v_mov_b32_e32 v87, v0
	v_mov_b32_e32 v96, v0
	v_mov_b32_e32 v97, v0
	v_mov_b32_e32 v98, v0
	v_mov_b32_e32 v99, v0
	v_mov_b32_e32 v100, v0
	v_mov_b32_e32 v101, v0
	v_mov_b32_e32 v102, v0
	v_mov_b32_e32 v103, v0
	v_mov_b32_e32 v112, v0
	v_mov_b32_e32 v113, v0
	v_mov_b32_e32 v114, v0
	v_mov_b32_e32 v115, v0
	v_mov_b32_e32 v116, v0
	v_mov_b32_e32 v117, v0
	v_mov_b32_e32 v118, v0
	v_mov_b32_e32 v119, v0
	v_mov_b32_e32 v120, v0
	v_mov_b32_e32 v121, v0
	v_mov_b32_e32 v122, v0
	v_mov_b32_e32 v123, v0
	v_mov_b32_e32 v124, v0
	v_mov_b32_e32 v125, v0
	v_mov_b32_e32 v126, v0
	v_mov_b32_e32 v127, v0
	.p2alignl 6, 3212836864

.LBB0_939:
	s_ashr_i32 s17, s16, 31
	s_lshl_b64 s[20:21], s[16:17], 19
	s_add_u32 s20, s36, s20
	s_addc_u32 s21, s37, s21
	s_and_b64 s[22:23], s[4:5], exec
	s_cselect_b32 s17, s21, s29
	s_cselect_b32 s25, s20, s28
	s_ashr_i32 s19, s18, 31
	s_lshl_b64 s[22:23], s[18:19], 19
	s_add_u32 s22, s38, s22
	s_addc_u32 s23, s39, s23
	s_and_b64 s[34:35], s[4:5], exec
	s_cselect_b32 s19, s23, s31
	s_cselect_b32 s27, s22, s30
	s_add_u32 s28, s28, 0x40080
	s_addc_u32 s29, s29, 0
	s_add_u32 s59, s30, 0x100
	v_mov_b32_e32 v0, 0
	s_addc_u32 s60, s31, 0
	s_mov_b32 s61, -2
	v_mov_b32_e32 v1, v0
	v_mov_b32_e32 v2, v0
	v_mov_b32_e32 v3, v0
	v_mov_b32_e32 v4, v0
	v_mov_b32_e32 v5, v0
	v_mov_b32_e32 v6, v0
	v_mov_b32_e32 v7, v0
	v_mov_b32_e32 v16, v0
	v_mov_b32_e32 v17, v0
	v_mov_b32_e32 v18, v0
	v_mov_b32_e32 v19, v0
	v_mov_b32_e32 v20, v0
	v_mov_b32_e32 v21, v0
	v_mov_b32_e32 v22, v0
	v_mov_b32_e32 v23, v0
	v_mov_b32_e32 v32, v0
	v_mov_b32_e32 v33, v0
	v_mov_b32_e32 v34, v0
	v_mov_b32_e32 v35, v0
	v_mov_b32_e32 v36, v0
	v_mov_b32_e32 v37, v0
	v_mov_b32_e32 v38, v0
	v_mov_b32_e32 v39, v0
	v_mov_b32_e32 v48, v0
	v_mov_b32_e32 v49, v0
	v_mov_b32_e32 v50, v0
	v_mov_b32_e32 v51, v0
	v_mov_b32_e32 v52, v0
	v_mov_b32_e32 v53, v0
	v_mov_b32_e32 v54, v0
	v_mov_b32_e32 v55, v0
	v_mov_b32_e32 v8, v0
	v_mov_b32_e32 v9, v0
	v_mov_b32_e32 v10, v0
	v_mov_b32_e32 v11, v0
	v_mov_b32_e32 v12, v0
	v_mov_b32_e32 v13, v0
	v_mov_b32_e32 v14, v0
	v_mov_b32_e32 v15, v0
	v_mov_b32_e32 v24, v0
	v_mov_b32_e32 v25, v0
	v_mov_b32_e32 v26, v0
	v_mov_b32_e32 v27, v0
	v_mov_b32_e32 v28, v0
	v_mov_b32_e32 v29, v0
	v_mov_b32_e32 v30, v0
	v_mov_b32_e32 v31, v0
	v_mov_b32_e32 v40, v0
	v_mov_b32_e32 v41, v0
	v_mov_b32_e32 v42, v0
	v_mov_b32_e32 v43, v0
	v_mov_b32_e32 v44, v0
	v_mov_b32_e32 v45, v0
	v_mov_b32_e32 v46, v0
	v_mov_b32_e32 v47, v0
	v_mov_b32_e32 v56, v0
	v_mov_b32_e32 v57, v0
	v_mov_b32_e32 v58, v0
	v_mov_b32_e32 v59, v0
	v_mov_b32_e32 v60, v0
	v_mov_b32_e32 v61, v0
	v_mov_b32_e32 v62, v0
	v_mov_b32_e32 v63, v0
	v_mov_b32_e32 v64, v0
	v_mov_b32_e32 v65, v0
	v_mov_b32_e32 v66, v0
	v_mov_b32_e32 v67, v0
	v_mov_b32_e32 v68, v0
	v_mov_b32_e32 v69, v0
	v_mov_b32_e32 v70, v0
	v_mov_b32_e32 v71, v0
	v_mov_b32_e32 v80, v0
	v_mov_b32_e32 v81, v0
	v_mov_b32_e32 v82, v0
	v_mov_b32_e32 v83, v0
	v_mov_b32_e32 v84, v0
	v_mov_b32_e32 v85, v0
	v_mov_b32_e32 v86, v0
	v_mov_b32_e32 v87, v0
	v_mov_b32_e32 v96, v0
	v_mov_b32_e32 v97, v0
	v_mov_b32_e32 v98, v0
	v_mov_b32_e32 v99, v0
	v_mov_b32_e32 v100, v0
	v_mov_b32_e32 v101, v0
	v_mov_b32_e32 v102, v0
	v_mov_b32_e32 v103, v0
	v_mov_b32_e32 v112, v0
	v_mov_b32_e32 v113, v0
	v_mov_b32_e32 v114, v0
	v_mov_b32_e32 v115, v0
	v_mov_b32_e32 v116, v0
	v_mov_b32_e32 v117, v0
	v_mov_b32_e32 v118, v0
	v_mov_b32_e32 v119, v0
	v_mov_b32_e32 v72, v0
	v_mov_b32_e32 v73, v0
	v_mov_b32_e32 v74, v0
	v_mov_b32_e32 v75, v0
	v_mov_b32_e32 v76, v0
	v_mov_b32_e32 v77, v0
	v_mov_b32_e32 v78, v0
	v_mov_b32_e32 v79, v0
	v_mov_b32_e32 v88, v0
	v_mov_b32_e32 v89, v0
	v_mov_b32_e32 v90, v0
	v_mov_b32_e32 v91, v0
	v_mov_b32_e32 v92, v0
	v_mov_b32_e32 v93, v0
	v_mov_b32_e32 v94, v0
	v_mov_b32_e32 v95, v0
	v_mov_b32_e32 v104, v0
	v_mov_b32_e32 v105, v0
	v_mov_b32_e32 v106, v0
	v_mov_b32_e32 v107, v0
	v_mov_b32_e32 v108, v0
	v_mov_b32_e32 v109, v0
	v_mov_b32_e32 v110, v0
	v_mov_b32_e32 v111, v0
	v_mov_b32_e32 v120, v0
	v_mov_b32_e32 v121, v0
	v_mov_b32_e32 v122, v0
	v_mov_b32_e32 v123, v0
	v_mov_b32_e32 v124, v0
	v_mov_b32_e32 v125, v0
	v_mov_b32_e32 v126, v0
	v_mov_b32_e32 v127, v0
	.p2alignl 6, 3212836864

.LBB0_1170:
	s_or_b64 exec, exec, s[0:1]
	s_andn2_b64 vcc, exec, s[90:91]
	s_xor_b32 s18, s18, 1
	s_cbranch_vccnz .LBB0_1182
	s_branch .LBB0_1036
	.p2alignl 6, 3212836864

.LBB0_1334:
	s_ashr_i32 s17, s16, 31
	s_lshl_b64 s[26:27], s[16:17], 19
	s_add_u32 s26, s42, s26
	s_addc_u32 s27, s43, s27
	s_and_b64 s[28:29], s[24:25], exec
	s_cselect_b32 s17, s27, s31
	s_cselect_b32 s21, s26, s30
	s_ashr_i32 s19, s18, 31
	s_lshl_b64 s[28:29], s[18:19], 19
	s_add_u32 s28, s44, s28
	s_addc_u32 s29, s45, s29
	s_and_b64 s[36:37], s[24:25], exec
	s_cselect_b32 s19, s29, s35
	s_cselect_b32 s57, s28, s34
	s_add_u32 s30, s30, 0x40080
	s_addc_u32 s31, s31, 0
	s_add_u32 s58, s34, 0x100
	v_mov_b32_e32 v0, 0
	s_addc_u32 s59, s35, 0
	s_mov_b32 s60, -2
	v_mov_b32_e32 v1, v0
	v_mov_b32_e32 v2, v0
	v_mov_b32_e32 v3, v0
	v_mov_b32_e32 v4, v0
	v_mov_b32_e32 v5, v0
	v_mov_b32_e32 v6, v0
	v_mov_b32_e32 v7, v0
	v_mov_b32_e32 v8, v0
	v_mov_b32_e32 v9, v0
	v_mov_b32_e32 v10, v0
	v_mov_b32_e32 v11, v0
	v_mov_b32_e32 v12, v0
	v_mov_b32_e32 v13, v0
	v_mov_b32_e32 v14, v0
	v_mov_b32_e32 v15, v0
	v_mov_b32_e32 v24, v0
	v_mov_b32_e32 v25, v0
	v_mov_b32_e32 v26, v0
	v_mov_b32_e32 v27, v0
	v_mov_b32_e32 v28, v0
	v_mov_b32_e32 v29, v0
	v_mov_b32_e32 v30, v0
	v_mov_b32_e32 v31, v0
	v_mov_b32_e32 v40, v0
	v_mov_b32_e32 v41, v0
	v_mov_b32_e32 v42, v0
	v_mov_b32_e32 v43, v0
	v_mov_b32_e32 v44, v0
	v_mov_b32_e32 v45, v0
	v_mov_b32_e32 v46, v0
	v_mov_b32_e32 v47, v0
	v_mov_b32_e32 v16, v0
	v_mov_b32_e32 v17, v0
	v_mov_b32_e32 v18, v0
	v_mov_b32_e32 v19, v0
	v_mov_b32_e32 v20, v0
	v_mov_b32_e32 v21, v0
	v_mov_b32_e32 v22, v0
	v_mov_b32_e32 v23, v0
	v_mov_b32_e32 v32, v0
	v_mov_b32_e32 v33, v0
	v_mov_b32_e32 v34, v0
	v_mov_b32_e32 v35, v0
	v_mov_b32_e32 v36, v0
	v_mov_b32_e32 v37, v0
	v_mov_b32_e32 v38, v0
	v_mov_b32_e32 v39, v0
	v_mov_b32_e32 v48, v0
	v_mov_b32_e32 v49, v0
	v_mov_b32_e32 v50, v0
	v_mov_b32_e32 v51, v0
	v_mov_b32_e32 v52, v0
	v_mov_b32_e32 v53, v0
	v_mov_b32_e32 v54, v0
	v_mov_b32_e32 v55, v0
	v_mov_b32_e32 v56, v0
	v_mov_b32_e32 v57, v0
	v_mov_b32_e32 v58, v0
	v_mov_b32_e32 v59, v0
	v_mov_b32_e32 v60, v0
	v_mov_b32_e32 v61, v0
	v_mov_b32_e32 v62, v0
	v_mov_b32_e32 v63, v0
	v_mov_b32_e32 v64, v0
	v_mov_b32_e32 v65, v0
	v_mov_b32_e32 v66, v0
	v_mov_b32_e32 v67, v0
	v_mov_b32_e32 v68, v0
	v_mov_b32_e32 v69, v0
	v_mov_b32_e32 v70, v0
	v_mov_b32_e32 v71, v0
	v_mov_b32_e32 v72, v0
	v_mov_b32_e32 v73, v0
	v_mov_b32_e32 v74, v0
	v_mov_b32_e32 v75, v0
	v_mov_b32_e32 v76, v0
	v_mov_b32_e32 v77, v0
	v_mov_b32_e32 v78, v0
	v_mov_b32_e32 v79, v0
	v_mov_b32_e32 v88, v0
	v_mov_b32_e32 v89, v0
	v_mov_b32_e32 v90, v0
	v_mov_b32_e32 v91, v0
	v_mov_b32_e32 v92, v0
	v_mov_b32_e32 v93, v0
	v_mov_b32_e32 v94, v0
	v_mov_b32_e32 v95, v0
	v_mov_b32_e32 v104, v0
	v_mov_b32_e32 v105, v0
	v_mov_b32_e32 v106, v0
	v_mov_b32_e32 v107, v0
	v_mov_b32_e32 v108, v0
	v_mov_b32_e32 v109, v0
	v_mov_b32_e32 v110, v0
	v_mov_b32_e32 v111, v0
	v_mov_b32_e32 v80, v0
	v_mov_b32_e32 v81, v0
	v_mov_b32_e32 v82, v0
	v_mov_b32_e32 v83, v0
	v_mov_b32_e32 v84, v0
	v_mov_b32_e32 v85, v0
	v_mov_b32_e32 v86, v0
	v_mov_b32_e32 v87, v0
	v_mov_b32_e32 v96, v0
	v_mov_b32_e32 v97, v0
	v_mov_b32_e32 v98, v0
	v_mov_b32_e32 v99, v0
	v_mov_b32_e32 v100, v0
	v_mov_b32_e32 v101, v0
	v_mov_b32_e32 v102, v0
	v_mov_b32_e32 v103, v0
	v_mov_b32_e32 v112, v0
	v_mov_b32_e32 v113, v0
	v_mov_b32_e32 v114, v0
	v_mov_b32_e32 v115, v0
	v_mov_b32_e32 v116, v0
	v_mov_b32_e32 v117, v0
	v_mov_b32_e32 v118, v0
	v_mov_b32_e32 v119, v0
	v_mov_b32_e32 v120, v0
	v_mov_b32_e32 v121, v0
	v_mov_b32_e32 v122, v0
	v_mov_b32_e32 v123, v0
	v_mov_b32_e32 v124, v0
	v_mov_b32_e32 v125, v0
	v_mov_b32_e32 v126, v0
	v_mov_b32_e32 v127, v0
	.p2alignl 6, 3212836864

.LBB0_1432:
	s_ashr_i32 s17, s16, 31
	s_lshl_b64 s[20:21], s[16:17], 19
	s_add_u32 s20, s30, s20
	s_addc_u32 s21, s31, s21
	s_and_b64 s[22:23], s[2:3], exec
	s_cselect_b32 s17, s21, s25
	s_cselect_b32 s50, s20, s24
	s_ashr_i32 s19, s18, 31
	s_lshl_b64 s[22:23], s[18:19], 19
	s_add_u32 s22, s34, s22
	s_addc_u32 s23, s35, s23
	s_and_b64 s[28:29], s[2:3], exec
	s_cselect_b32 s19, s23, s27
	s_cselect_b32 s51, s22, s26
	s_add_u32 s24, s24, 0x40080
	s_addc_u32 s25, s25, 0
	s_add_u32 s52, s26, 0x100
	v_mov_b32_e32 v0, 0
	s_addc_u32 s53, s27, 0
	s_mov_b32 s54, -2
	v_mov_b32_e32 v1, v0
	v_mov_b32_e32 v2, v0
	v_mov_b32_e32 v3, v0
	v_mov_b32_e32 v4, v0
	v_mov_b32_e32 v5, v0
	v_mov_b32_e32 v6, v0
	v_mov_b32_e32 v7, v0
	v_mov_b32_e32 v8, v0
	v_mov_b32_e32 v9, v0
	v_mov_b32_e32 v10, v0
	v_mov_b32_e32 v11, v0
	v_mov_b32_e32 v12, v0
	v_mov_b32_e32 v13, v0
	v_mov_b32_e32 v14, v0
	v_mov_b32_e32 v15, v0
	v_mov_b32_e32 v24, v0
	v_mov_b32_e32 v25, v0
	v_mov_b32_e32 v26, v0
	v_mov_b32_e32 v27, v0
	v_mov_b32_e32 v28, v0
	v_mov_b32_e32 v29, v0
	v_mov_b32_e32 v30, v0
	v_mov_b32_e32 v31, v0
	v_mov_b32_e32 v40, v0
	v_mov_b32_e32 v41, v0
	v_mov_b32_e32 v42, v0
	v_mov_b32_e32 v43, v0
	v_mov_b32_e32 v44, v0
	v_mov_b32_e32 v45, v0
	v_mov_b32_e32 v46, v0
	v_mov_b32_e32 v47, v0
	v_mov_b32_e32 v16, v0
	v_mov_b32_e32 v17, v0
	v_mov_b32_e32 v18, v0
	v_mov_b32_e32 v19, v0
	v_mov_b32_e32 v20, v0
	v_mov_b32_e32 v21, v0
	v_mov_b32_e32 v22, v0
	v_mov_b32_e32 v23, v0
	v_mov_b32_e32 v32, v0
	v_mov_b32_e32 v33, v0
	v_mov_b32_e32 v34, v0
	v_mov_b32_e32 v35, v0
	v_mov_b32_e32 v36, v0
	v_mov_b32_e32 v37, v0
	v_mov_b32_e32 v38, v0
	v_mov_b32_e32 v39, v0
	v_mov_b32_e32 v48, v0
	v_mov_b32_e32 v49, v0
	v_mov_b32_e32 v50, v0
	v_mov_b32_e32 v51, v0
	v_mov_b32_e32 v52, v0
	v_mov_b32_e32 v53, v0
	v_mov_b32_e32 v54, v0
	v_mov_b32_e32 v55, v0
	v_mov_b32_e32 v56, v0
	v_mov_b32_e32 v57, v0
	v_mov_b32_e32 v58, v0
	v_mov_b32_e32 v59, v0
	v_mov_b32_e32 v60, v0
	v_mov_b32_e32 v61, v0
	v_mov_b32_e32 v62, v0
	v_mov_b32_e32 v63, v0
	v_mov_b32_e32 v64, v0
	v_mov_b32_e32 v65, v0
	v_mov_b32_e32 v66, v0
	v_mov_b32_e32 v67, v0
	v_mov_b32_e32 v68, v0
	v_mov_b32_e32 v69, v0
	v_mov_b32_e32 v70, v0
	v_mov_b32_e32 v71, v0
	v_mov_b32_e32 v72, v0
	v_mov_b32_e32 v73, v0
	v_mov_b32_e32 v74, v0
	v_mov_b32_e32 v75, v0
	v_mov_b32_e32 v76, v0
	v_mov_b32_e32 v77, v0
	v_mov_b32_e32 v78, v0
	v_mov_b32_e32 v79, v0
	v_mov_b32_e32 v88, v0
	v_mov_b32_e32 v89, v0
	v_mov_b32_e32 v90, v0
	v_mov_b32_e32 v91, v0
	v_mov_b32_e32 v92, v0
	v_mov_b32_e32 v93, v0
	v_mov_b32_e32 v94, v0
	v_mov_b32_e32 v95, v0
	v_mov_b32_e32 v104, v0
	v_mov_b32_e32 v105, v0
	v_mov_b32_e32 v106, v0
	v_mov_b32_e32 v107, v0
	v_mov_b32_e32 v108, v0
	v_mov_b32_e32 v109, v0
	v_mov_b32_e32 v110, v0
	v_mov_b32_e32 v111, v0
	v_mov_b32_e32 v80, v0
	v_mov_b32_e32 v81, v0
	v_mov_b32_e32 v82, v0
	v_mov_b32_e32 v83, v0
	v_mov_b32_e32 v84, v0
	v_mov_b32_e32 v85, v0
	v_mov_b32_e32 v86, v0
	v_mov_b32_e32 v87, v0
	v_mov_b32_e32 v96, v0
	v_mov_b32_e32 v97, v0
	v_mov_b32_e32 v98, v0
	v_mov_b32_e32 v99, v0
	v_mov_b32_e32 v100, v0
	v_mov_b32_e32 v101, v0
	v_mov_b32_e32 v102, v0
	v_mov_b32_e32 v103, v0
	v_mov_b32_e32 v112, v0
	v_mov_b32_e32 v113, v0
	v_mov_b32_e32 v114, v0
	v_mov_b32_e32 v115, v0
	v_mov_b32_e32 v116, v0
	v_mov_b32_e32 v117, v0
	v_mov_b32_e32 v118, v0
	v_mov_b32_e32 v119, v0
	v_mov_b32_e32 v120, v0
	v_mov_b32_e32 v121, v0
	v_mov_b32_e32 v122, v0
	v_mov_b32_e32 v123, v0
	v_mov_b32_e32 v124, v0
	v_mov_b32_e32 v125, v0
	v_mov_b32_e32 v126, v0
	v_mov_b32_e32 v127, v0
	.p2alignl 6, 3212836864

.LBB0_1520:
	s_or_b64 exec, exec, s[0:1]
	s_add_i32 s6, s6, 1
	s_cmp_ge_i32 s6, s7
	s_waitcnt lgkmcnt(0)
	s_barrier
	s_cbranch_scc1 .LBB0_1503
	.p2alignl 6, 3212836864

.LBB0_1672:
	s_lshl_b32 s1, s39, 2
	s_sub_i32 s0, s38, s1
	s_sub_i32 s1, s40, s1
	s_max_i32 s0, s0, 0
	s_min_i32 s1, s1, 4
	s_cmp_ge_i32 s0, s1
	s_waitcnt lgkmcnt(0)
	s_barrier
	s_cbranch_scc1 .LBB0_1657
	s_mulk_i32 s66, 0x84
	v_add_u32_e32 v198, s68, v161
	v_or_b32_e32 v199, 64, v196
	v_or_b32_e32 v200, 0x80, v196
	v_or_b32_e32 v201, 0xc0, v196
	v_lshl_add_u64 v[178:179], v[64:65], 2, s[42:43]
	v_lshl_add_u64 v[180:181], v[166:167], 0, s[70:71]
	v_lshl_add_u64 v[182:183], v[162:163], 0, s[70:71]
	s_add_i32 s12, s67, s66
	.p2alignl 6, 3212836864

.LBB0_1746:
	s_add_u32 s16, s16, 0x50080
	s_addc_u32 s17, s17, 0
	s_add_u32 s47, s18, 0x100
	v_mov_b32_e32 v0, 0
	s_addc_u32 s48, s19, 0
	s_mov_b32 s49, -2
	v_mov_b32_e32 v1, v0
	v_mov_b32_e32 v2, v0
	v_mov_b32_e32 v3, v0
	v_mov_b32_e32 v4, v0
	v_mov_b32_e32 v5, v0
	v_mov_b32_e32 v6, v0
	v_mov_b32_e32 v7, v0
	v_mov_b32_e32 v8, v0
	v_mov_b32_e32 v9, v0
	v_mov_b32_e32 v10, v0
	v_mov_b32_e32 v11, v0
	v_mov_b32_e32 v12, v0
	v_mov_b32_e32 v13, v0
	v_mov_b32_e32 v14, v0
	v_mov_b32_e32 v15, v0
	v_mov_b32_e32 v24, v0
	v_mov_b32_e32 v25, v0
	v_mov_b32_e32 v26, v0
	v_mov_b32_e32 v27, v0
	v_mov_b32_e32 v28, v0
	v_mov_b32_e32 v29, v0
	v_mov_b32_e32 v30, v0
	v_mov_b32_e32 v31, v0
	v_mov_b32_e32 v40, v0
	v_mov_b32_e32 v41, v0
	v_mov_b32_e32 v42, v0
	v_mov_b32_e32 v43, v0
	v_mov_b32_e32 v44, v0
	v_mov_b32_e32 v45, v0
	v_mov_b32_e32 v46, v0
	v_mov_b32_e32 v47, v0
	v_mov_b32_e32 v16, v0
	v_mov_b32_e32 v17, v0
	v_mov_b32_e32 v18, v0
	v_mov_b32_e32 v19, v0
	v_mov_b32_e32 v20, v0
	v_mov_b32_e32 v21, v0
	v_mov_b32_e32 v22, v0
	v_mov_b32_e32 v23, v0
	v_mov_b32_e32 v32, v0
	v_mov_b32_e32 v33, v0
	v_mov_b32_e32 v34, v0
	v_mov_b32_e32 v35, v0
	v_mov_b32_e32 v36, v0
	v_mov_b32_e32 v37, v0
	v_mov_b32_e32 v38, v0
	v_mov_b32_e32 v39, v0
	v_mov_b32_e32 v48, v0
	v_mov_b32_e32 v49, v0
	v_mov_b32_e32 v50, v0
	v_mov_b32_e32 v51, v0
	v_mov_b32_e32 v52, v0
	v_mov_b32_e32 v53, v0
	v_mov_b32_e32 v54, v0
	v_mov_b32_e32 v55, v0
	v_mov_b32_e32 v56, v0
	v_mov_b32_e32 v57, v0
	v_mov_b32_e32 v58, v0
	v_mov_b32_e32 v59, v0
	v_mov_b32_e32 v60, v0
	v_mov_b32_e32 v61, v0
	v_mov_b32_e32 v62, v0
	v_mov_b32_e32 v63, v0
	v_mov_b32_e32 v64, v0
	v_mov_b32_e32 v65, v0
	v_mov_b32_e32 v66, v0
	v_mov_b32_e32 v67, v0
	v_mov_b32_e32 v68, v0
	v_mov_b32_e32 v69, v0
	v_mov_b32_e32 v70, v0
	v_mov_b32_e32 v71, v0
	v_mov_b32_e32 v72, v0
	v_mov_b32_e32 v73, v0
	v_mov_b32_e32 v74, v0
	v_mov_b32_e32 v75, v0
	v_mov_b32_e32 v76, v0
	v_mov_b32_e32 v77, v0
	v_mov_b32_e32 v78, v0
	v_mov_b32_e32 v79, v0
	v_mov_b32_e32 v88, v0
	v_mov_b32_e32 v89, v0
	v_mov_b32_e32 v90, v0
	v_mov_b32_e32 v91, v0
	v_mov_b32_e32 v92, v0
	v_mov_b32_e32 v93, v0
	v_mov_b32_e32 v94, v0
	v_mov_b32_e32 v95, v0
	v_mov_b32_e32 v104, v0
	v_mov_b32_e32 v105, v0
	v_mov_b32_e32 v106, v0
	v_mov_b32_e32 v107, v0
	v_mov_b32_e32 v108, v0
	v_mov_b32_e32 v109, v0
	v_mov_b32_e32 v110, v0
	v_mov_b32_e32 v111, v0
	v_mov_b32_e32 v80, v0
	v_mov_b32_e32 v81, v0
	v_mov_b32_e32 v82, v0
	v_mov_b32_e32 v83, v0
	v_mov_b32_e32 v84, v0
	v_mov_b32_e32 v85, v0
	v_mov_b32_e32 v86, v0
	v_mov_b32_e32 v87, v0
	v_mov_b32_e32 v96, v0
	v_mov_b32_e32 v97, v0
	v_mov_b32_e32 v98, v0
	v_mov_b32_e32 v99, v0
	v_mov_b32_e32 v100, v0
	v_mov_b32_e32 v101, v0
	v_mov_b32_e32 v102, v0
	v_mov_b32_e32 v103, v0
	v_mov_b32_e32 v112, v0
	v_mov_b32_e32 v113, v0
	v_mov_b32_e32 v114, v0
	v_mov_b32_e32 v115, v0
	v_mov_b32_e32 v116, v0
	v_mov_b32_e32 v117, v0
	v_mov_b32_e32 v118, v0
	v_mov_b32_e32 v119, v0
	v_mov_b32_e32 v120, v0
	v_mov_b32_e32 v121, v0
	v_mov_b32_e32 v122, v0
	v_mov_b32_e32 v123, v0
	v_mov_b32_e32 v124, v0
	v_mov_b32_e32 v125, v0
	v_mov_b32_e32 v126, v0
	v_mov_b32_e32 v127, v0
	.p2alignl 6, 3212836864

.LBB0_1830:
	s_add_u32 s22, s22, 0x50080
	s_addc_u32 s23, s23, 0
	s_add_u32 s56, s24, 0x100
	v_mov_b32_e32 v0, 0
	s_addc_u32 s57, s25, 0
	s_mov_b32 s58, -2
	v_mov_b32_e32 v1, v0
	v_mov_b32_e32 v2, v0
	v_mov_b32_e32 v3, v0
	v_mov_b32_e32 v4, v0
	v_mov_b32_e32 v5, v0
	v_mov_b32_e32 v6, v0
	v_mov_b32_e32 v7, v0
	v_mov_b32_e32 v8, v0
	v_mov_b32_e32 v9, v0
	v_mov_b32_e32 v10, v0
	v_mov_b32_e32 v11, v0
	v_mov_b32_e32 v12, v0
	v_mov_b32_e32 v13, v0
	v_mov_b32_e32 v14, v0
	v_mov_b32_e32 v15, v0
	v_mov_b32_e32 v24, v0
	v_mov_b32_e32 v25, v0
	v_mov_b32_e32 v26, v0
	v_mov_b32_e32 v27, v0
	v_mov_b32_e32 v28, v0
	v_mov_b32_e32 v29, v0
	v_mov_b32_e32 v30, v0
	v_mov_b32_e32 v31, v0
	v_mov_b32_e32 v40, v0
	v_mov_b32_e32 v41, v0
	v_mov_b32_e32 v42, v0
	v_mov_b32_e32 v43, v0
	v_mov_b32_e32 v44, v0
	v_mov_b32_e32 v45, v0
	v_mov_b32_e32 v46, v0
	v_mov_b32_e32 v47, v0
	v_mov_b32_e32 v16, v0
	v_mov_b32_e32 v17, v0
	v_mov_b32_e32 v18, v0
	v_mov_b32_e32 v19, v0
	v_mov_b32_e32 v20, v0
	v_mov_b32_e32 v21, v0
	v_mov_b32_e32 v22, v0
	v_mov_b32_e32 v23, v0
	v_mov_b32_e32 v32, v0
	v_mov_b32_e32 v33, v0
	v_mov_b32_e32 v34, v0
	v_mov_b32_e32 v35, v0
	v_mov_b32_e32 v36, v0
	v_mov_b32_e32 v37, v0
	v_mov_b32_e32 v38, v0
	v_mov_b32_e32 v39, v0
	v_mov_b32_e32 v48, v0
	v_mov_b32_e32 v49, v0
	v_mov_b32_e32 v50, v0
	v_mov_b32_e32 v51, v0
	v_mov_b32_e32 v52, v0
	v_mov_b32_e32 v53, v0
	v_mov_b32_e32 v54, v0
	v_mov_b32_e32 v55, v0
	v_mov_b32_e32 v56, v0
	v_mov_b32_e32 v57, v0
	v_mov_b32_e32 v58, v0
	v_mov_b32_e32 v59, v0
	v_mov_b32_e32 v60, v0
	v_mov_b32_e32 v61, v0
	v_mov_b32_e32 v62, v0
	v_mov_b32_e32 v63, v0
	v_mov_b32_e32 v64, v0
	v_mov_b32_e32 v65, v0
	v_mov_b32_e32 v66, v0
	v_mov_b32_e32 v67, v0
	v_mov_b32_e32 v68, v0
	v_mov_b32_e32 v69, v0
	v_mov_b32_e32 v70, v0
	v_mov_b32_e32 v71, v0
	v_mov_b32_e32 v72, v0
	v_mov_b32_e32 v73, v0
	v_mov_b32_e32 v74, v0
	v_mov_b32_e32 v75, v0
	v_mov_b32_e32 v76, v0
	v_mov_b32_e32 v77, v0
	v_mov_b32_e32 v78, v0
	v_mov_b32_e32 v79, v0
	v_mov_b32_e32 v88, v0
	v_mov_b32_e32 v89, v0
	v_mov_b32_e32 v90, v0
	v_mov_b32_e32 v91, v0
	v_mov_b32_e32 v92, v0
	v_mov_b32_e32 v93, v0
	v_mov_b32_e32 v94, v0
	v_mov_b32_e32 v95, v0
	v_mov_b32_e32 v104, v0
	v_mov_b32_e32 v105, v0
	v_mov_b32_e32 v106, v0
	v_mov_b32_e32 v107, v0
	v_mov_b32_e32 v108, v0
	v_mov_b32_e32 v109, v0
	v_mov_b32_e32 v110, v0
	v_mov_b32_e32 v111, v0
	v_mov_b32_e32 v80, v0
	v_mov_b32_e32 v81, v0
	v_mov_b32_e32 v82, v0
	v_mov_b32_e32 v83, v0
	v_mov_b32_e32 v84, v0
	v_mov_b32_e32 v85, v0
	v_mov_b32_e32 v86, v0
	v_mov_b32_e32 v87, v0
	v_mov_b32_e32 v96, v0
	v_mov_b32_e32 v97, v0
	v_mov_b32_e32 v98, v0
	v_mov_b32_e32 v99, v0
	v_mov_b32_e32 v100, v0
	v_mov_b32_e32 v101, v0
	v_mov_b32_e32 v102, v0
	v_mov_b32_e32 v103, v0
	v_mov_b32_e32 v112, v0
	v_mov_b32_e32 v113, v0
	v_mov_b32_e32 v114, v0
	v_mov_b32_e32 v115, v0
	v_mov_b32_e32 v116, v0
	v_mov_b32_e32 v117, v0
	v_mov_b32_e32 v118, v0
	v_mov_b32_e32 v119, v0
	v_mov_b32_e32 v120, v0
	v_mov_b32_e32 v121, v0
	v_mov_b32_e32 v122, v0
	v_mov_b32_e32 v123, v0
	v_mov_b32_e32 v124, v0
	v_mov_b32_e32 v125, v0
	v_mov_b32_e32 v126, v0
	v_mov_b32_e32 v127, v0
	.p2alignl 6, 3212836864

.LBB0_1928:
	s_ashr_i32 s19, s18, 31
	s_lshl_b64 s[22:23], s[18:19], 19
	s_add_u32 s22, s34, s22
	s_addc_u32 s23, s35, s23
	s_and_b64 s[24:25], s[2:3], exec
	s_cselect_b32 s5, s23, s27
	s_cselect_b32 s7, s22, s26
	s_ashr_i32 s21, s20, 31
	s_lshl_b64 s[24:25], s[20:21], 19
	s_add_u32 s24, s36, s24
	s_addc_u32 s25, s37, s25
	s_and_b64 s[30:31], s[2:3], exec
	s_cselect_b32 s19, s25, s29
	s_cselect_b32 s21, s24, s28
	s_add_u32 s26, s26, 0x40080
	s_addc_u32 s27, s27, 0
	s_add_u32 s56, s28, 0x100
	v_mov_b32_e32 v0, 0
	s_addc_u32 s57, s29, 0
	s_mov_b32 s58, -2
	v_mov_b32_e32 v1, v0
	v_mov_b32_e32 v2, v0
	v_mov_b32_e32 v3, v0
	v_mov_b32_e32 v4, v0
	v_mov_b32_e32 v5, v0
	v_mov_b32_e32 v6, v0
	v_mov_b32_e32 v7, v0
	v_mov_b32_e32 v16, v0
	v_mov_b32_e32 v17, v0
	v_mov_b32_e32 v18, v0
	v_mov_b32_e32 v19, v0
	v_mov_b32_e32 v20, v0
	v_mov_b32_e32 v21, v0
	v_mov_b32_e32 v22, v0
	v_mov_b32_e32 v23, v0
	v_mov_b32_e32 v32, v0
	v_mov_b32_e32 v33, v0
	v_mov_b32_e32 v34, v0
	v_mov_b32_e32 v35, v0
	v_mov_b32_e32 v36, v0
	v_mov_b32_e32 v37, v0
	v_mov_b32_e32 v38, v0
	v_mov_b32_e32 v39, v0
	v_mov_b32_e32 v48, v0
	v_mov_b32_e32 v49, v0
	v_mov_b32_e32 v50, v0
	v_mov_b32_e32 v51, v0
	v_mov_b32_e32 v52, v0
	v_mov_b32_e32 v53, v0
	v_mov_b32_e32 v54, v0
	v_mov_b32_e32 v55, v0
	v_mov_b32_e32 v8, v0
	v_mov_b32_e32 v9, v0
	v_mov_b32_e32 v10, v0
	v_mov_b32_e32 v11, v0
	v_mov_b32_e32 v12, v0
	v_mov_b32_e32 v13, v0
	v_mov_b32_e32 v14, v0
	v_mov_b32_e32 v15, v0
	v_mov_b32_e32 v24, v0
	v_mov_b32_e32 v25, v0
	v_mov_b32_e32 v26, v0
	v_mov_b32_e32 v27, v0
	v_mov_b32_e32 v28, v0
	v_mov_b32_e32 v29, v0
	v_mov_b32_e32 v30, v0
	v_mov_b32_e32 v31, v0
	v_mov_b32_e32 v40, v0
	v_mov_b32_e32 v41, v0
	v_mov_b32_e32 v42, v0
	v_mov_b32_e32 v43, v0
	v_mov_b32_e32 v44, v0
	v_mov_b32_e32 v45, v0
	v_mov_b32_e32 v46, v0
	v_mov_b32_e32 v47, v0
	v_mov_b32_e32 v56, v0
	v_mov_b32_e32 v57, v0
	v_mov_b32_e32 v58, v0
	v_mov_b32_e32 v59, v0
	v_mov_b32_e32 v60, v0
	v_mov_b32_e32 v61, v0
	v_mov_b32_e32 v62, v0
	v_mov_b32_e32 v63, v0
	v_mov_b32_e32 v64, v0
	v_mov_b32_e32 v65, v0
	v_mov_b32_e32 v66, v0
	v_mov_b32_e32 v67, v0
	v_mov_b32_e32 v68, v0
	v_mov_b32_e32 v69, v0
	v_mov_b32_e32 v70, v0
	v_mov_b32_e32 v71, v0
	v_mov_b32_e32 v80, v0
	v_mov_b32_e32 v81, v0
	v_mov_b32_e32 v82, v0
	v_mov_b32_e32 v83, v0
	v_mov_b32_e32 v84, v0
	v_mov_b32_e32 v85, v0
	v_mov_b32_e32 v86, v0
	v_mov_b32_e32 v87, v0
	v_mov_b32_e32 v96, v0
	v_mov_b32_e32 v97, v0
	v_mov_b32_e32 v98, v0
	v_mov_b32_e32 v99, v0
	v_mov_b32_e32 v100, v0
	v_mov_b32_e32 v101, v0
	v_mov_b32_e32 v102, v0
	v_mov_b32_e32 v103, v0
	v_mov_b32_e32 v112, v0
	v_mov_b32_e32 v113, v0
	v_mov_b32_e32 v114, v0
	v_mov_b32_e32 v115, v0
	v_mov_b32_e32 v116, v0
	v_mov_b32_e32 v117, v0
	v_mov_b32_e32 v118, v0
	v_mov_b32_e32 v119, v0
	v_mov_b32_e32 v72, v0
	v_mov_b32_e32 v73, v0
	v_mov_b32_e32 v74, v0
	v_mov_b32_e32 v75, v0
	v_mov_b32_e32 v76, v0
	v_mov_b32_e32 v77, v0
	v_mov_b32_e32 v78, v0
	v_mov_b32_e32 v79, v0
	v_mov_b32_e32 v88, v0
	v_mov_b32_e32 v89, v0
	v_mov_b32_e32 v90, v0
	v_mov_b32_e32 v91, v0
	v_mov_b32_e32 v92, v0
	v_mov_b32_e32 v93, v0
	v_mov_b32_e32 v94, v0
	v_mov_b32_e32 v95, v0
	v_mov_b32_e32 v104, v0
	v_mov_b32_e32 v105, v0
	v_mov_b32_e32 v106, v0
	v_mov_b32_e32 v107, v0
	v_mov_b32_e32 v108, v0
	v_mov_b32_e32 v109, v0
	v_mov_b32_e32 v110, v0
	v_mov_b32_e32 v111, v0
	v_mov_b32_e32 v120, v0
	v_mov_b32_e32 v121, v0
	v_mov_b32_e32 v122, v0
	v_mov_b32_e32 v123, v0
	v_mov_b32_e32 v124, v0
	v_mov_b32_e32 v125, v0
	v_mov_b32_e32 v126, v0
	v_mov_b32_e32 v127, v0
	.p2alignl 6, 3212836864
